# same pointer-select SALU move (phase 0 -> phase 1 load segment) for the six fixed-round GEMM loops (MLP-down, out-proj)
# speedup vs baseline: 1.0170x; 1.0023x over previous
; #define PG8_STAGE(bufoff, gbase, voff) do { _Pragma("unroll") for (int _i = 0; _i < 2; ++_i) \
;         __builtin_amdgcn_global_load_lds((const unsigned*)((const char*)(gbase) + (voff)[_i]), (LAS unsigned*)(lds + (bufoff) + ldsw + _i * 8192), 16, 0, 0); } while (0)
; #define PG8_LDA(dst, b, h) do { _Pragma("unroll") for (int m = 0; m < 4; ++m) _Pragma("unroll") for (int k = 0; k < 2; ++k) dst[m][k] = *(const LAS bf16x8*)(lds + PG8_SA(b, h) + aoff + m * 2048 + k * 1024); } while (0)
; #define PG8_LDB(dst, b, h) do { _Pragma("unroll") for (int n = 0; n < 2; ++n) _Pragma("unroll") for (int k = 0; k < 2; ++k) dst[n][k] = *(const LAS bf16x8*)(lds + PG8_SB(b, h) + boff + n * 2048 + k * 1024); } while (0)
; #define PG8_WAIT_V(n) asm volatile("s_waitcnt vmcnt(" #n ")" ::: "memory")
; #define PG8_WAIT_L(n) asm volatile("s_waitcnt lgkmcnt(" #n ")" ::: "memory")
; #define PG8_BAR __builtin_amdgcn_s_barrier()
; #define PG8_SCHED __builtin_amdgcn_sched_barrier(0)
; template <class Epi>
; __device__ __forceinline__ void gemm_phase(LAS unsigned char* lds, const bf16_t* A, int lda, const bf16_t* Bt, int ldb, int M, int N, int K, int asel, const Epi& E, const int fixed_round = -1) {
;     ...
;         const char* nA = has_next ? PG8_ABASE(nxt) : cA; const char* nB = has_next ? (const char*)Bt + (size_t)nxt.pn * tstepB : cB;
;         for (int t = 0; t < nt; t += 2) {
;             const bool last = (t == nt - 2);
;             const char* a1 = cA + (size_t)(t + 1) * kstep;
;             const char* a2 = last ? nA : cA + (size_t)(t + 2) * kstep; const char* b2 = last ? nB : cB + (size_t)(t + 2) * kstep;
;             const char* a3 = a2 + kstep; const char* b3 = b2 + kstep;
;             PG8_LDB(B0, 0, 0); PG8_SCHED; PG8_LDA(At, 0, 0); PG8_STAGE(PG8_SA(1, 1), a1 + hstepA, voffA);
;             PG8_WAIT_L(8); PG8_BAR; PG8_WAIT_L(0); PG8_MMA(0, 0, At, B0); PG8_BAR; PG8_SCHED;
;             PG8_LDB(B1, 0, 1); PG8_STAGE(PG8_SB(0, 0), b2, voffB);
;             PG8_BAR; PG8_WAIT_L(0); PG8_MMA(0, 1, At, B1); PG8_BAR;
;             PG8_LDA(At, 0, 1); PG8_STAGE(PG8_SA(0, 0), a2, voffA);
;             PG8_BAR; PG8_WAIT_L(0); PG8_MMA(1, 0, At, B0); PG8_BAR; PG8_SCHED;
;             PG8_STAGE(PG8_SB(0, 1), b2 + hstepB, voffB);
;             PG8_WAIT_V(6); PG8_BAR; PG8_MMA(1, 1, At, B1); PG8_BAR;
.LBB0_651:
	ds_read_b128 v[146:149], v140
	ds_read_b128 v[150:153], v140 offset:1024
	ds_read_b128 v[160:163], v140 offset:2048
	ds_read_b128 v[166:169], v140 offset:3072
	s_mov_b32 m0, s49
	v_lshl_add_u64 v[156:157], v[136:137], 0, s[20:21]
	ds_read_b128 v[170:173], v141
	ds_read_b128 v[174:177], v141 offset:1024
	ds_read_b128 v[178:181], v141 offset:2048
	ds_read_b128 v[182:185], v141 offset:3072
	ds_read_b128 v[186:189], v141 offset:4096
	ds_read_b128 v[190:193], v141 offset:5120
	ds_read_b128 v[194:197], v141 offset:6144
	ds_read_b128 v[202:205], v141 offset:7168
	global_load_lds_dwordx4 v[156:157], off
	v_lshl_add_u64 v[156:157], v[138:139], 0, s[20:21]
	s_mov_b32 m0, s50
	s_nop 0
	global_load_lds_dwordx4 v[156:157], off
	s_waitcnt lgkmcnt(8)
	s_barrier
	s_waitcnt lgkmcnt(0)
	s_setprio 1
	s_waitcnt lgkmcnt(0)
	v_mfma_f32_16x16x32_bf16 v[124:127], v[146:149], v[170:173], v[124:127]
	v_mfma_f32_16x16x32_bf16 v[120:123], v[160:163], v[170:173], v[120:123]
	v_mfma_f32_16x16x32_bf16 v[112:115], v[146:149], v[178:181], v[112:115]
	v_mfma_f32_16x16x32_bf16 v[104:107], v[160:163], v[178:181], v[104:107]
	v_mfma_f32_16x16x32_bf16 v[96:99], v[146:149], v[186:189], v[96:99]
	v_mfma_f32_16x16x32_bf16 v[88:91], v[160:163], v[186:189], v[88:91]
	v_mfma_f32_16x16x32_bf16 v[80:83], v[146:149], v[194:197], v[80:83]
	v_mfma_f32_16x16x32_bf16 v[72:75], v[160:163], v[194:197], v[72:75]
	v_mfma_f32_16x16x32_bf16 v[124:127], v[150:153], v[174:177], v[124:127]
	v_mfma_f32_16x16x32_bf16 v[120:123], v[166:169], v[174:177], v[120:123]
	v_mfma_f32_16x16x32_bf16 v[112:115], v[150:153], v[182:185], v[112:115]
	v_mfma_f32_16x16x32_bf16 v[104:107], v[166:169], v[182:185], v[104:107]
	v_mfma_f32_16x16x32_bf16 v[96:99], v[150:153], v[190:193], v[96:99]
	v_mfma_f32_16x16x32_bf16 v[88:91], v[166:169], v[190:193], v[88:91]
	v_mfma_f32_16x16x32_bf16 v[80:83], v[150:153], v[202:205], v[80:83]
	v_mfma_f32_16x16x32_bf16 v[72:75], v[166:169], v[202:205], v[72:75]
	s_setprio 0
	s_barrier
	s_add_u32 s28, s20, 0xe7900080
	s_addc_u32 s29, s21, -1
	s_cmpk_lg_i32 s48, 0x7c
	s_cselect_b32 s28, s28, 0
	s_cselect_b32 s29, s29, 0
	s_add_u32 s36, s86, s28
	s_addc_u32 s37, s87, s29
	s_add_u32 s34, s2, s28
	s_addc_u32 s35, s3, s29
	s_mov_b32 m0, s51
	s_add_u32 s98, s34, s0
	s_addc_u32 s99, s35, s1
	ds_read_b128 v[206:209], v142
	ds_read_b128 v[210:213], v142 offset:1024
	ds_read_b128 v[214:217], v142 offset:2048
	ds_read_b128 v[218:221], v142 offset:3072
	global_load_lds_dwordx4 v130, s[34:35]
	s_mov_b32 m0, s52
	s_nop 0
	global_load_lds_dwordx4 v134, s[34:35]
	s_barrier
	s_waitcnt lgkmcnt(0)
	s_setprio 1
	s_waitcnt lgkmcnt(0)
	v_mfma_f32_16x16x32_bf16 v[116:119], v[206:209], v[170:173], v[116:119]
	v_mfma_f32_16x16x32_bf16 v[108:111], v[214:217], v[170:173], v[108:111]
	v_mfma_f32_16x16x32_bf16 v[100:103], v[206:209], v[178:181], v[100:103]
	v_mfma_f32_16x16x32_bf16 v[92:95], v[214:217], v[178:181], v[92:95]
	v_mfma_f32_16x16x32_bf16 v[84:87], v[206:209], v[186:189], v[84:87]
	v_mfma_f32_16x16x32_bf16 v[76:79], v[214:217], v[186:189], v[76:79]
	v_mfma_f32_16x16x32_bf16 v[68:71], v[206:209], v[194:197], v[68:71]
	v_mfma_f32_16x16x32_bf16 v[64:67], v[214:217], v[194:197], v[64:67]
	v_mfma_f32_16x16x32_bf16 v[116:119], v[210:213], v[174:177], v[116:119]
	v_mfma_f32_16x16x32_bf16 v[108:111], v[218:221], v[174:177], v[108:111]
	v_mfma_f32_16x16x32_bf16 v[100:103], v[210:213], v[182:185], v[100:103]
	v_mfma_f32_16x16x32_bf16 v[92:95], v[218:221], v[182:185], v[92:95]
	v_mfma_f32_16x16x32_bf16 v[84:87], v[210:213], v[190:193], v[84:87]
	v_mfma_f32_16x16x32_bf16 v[76:79], v[218:221], v[190:193], v[76:79]
	v_mfma_f32_16x16x32_bf16 v[68:71], v[210:213], v[202:205], v[68:71]
	v_mfma_f32_16x16x32_bf16 v[64:67], v[218:221], v[202:205], v[64:67]
	s_setprio 0
	s_mov_b32 m0, s42
	s_add_u32 s100, s36, s0
	s_addc_u32 s101, s37, s1
	s_barrier
	ds_read_b128 v[170:173], v141 offset:16384
	ds_read_b128 v[174:177], v141 offset:17408
	ds_read_b128 v[178:181], v141 offset:18432
	ds_read_b128 v[182:185], v141 offset:19456
	ds_read_b128 v[186:189], v141 offset:20480
	ds_read_b128 v[190:193], v141 offset:21504
	ds_read_b128 v[194:197], v141 offset:22528
	ds_read_b128 v[202:205], v141 offset:23552
	global_load_lds_dwordx4 v128, s[36:37]
	s_mov_b32 m0, s43
	s_nop 0
	global_load_lds_dwordx4 v132, s[36:37]
	s_barrier
	s_waitcnt lgkmcnt(0)
	s_setprio 1
	s_waitcnt lgkmcnt(0)
	v_mfma_f32_16x16x32_bf16 v[60:63], v[146:149], v[170:173], v[60:63]
	v_mfma_f32_16x16x32_bf16 v[56:59], v[160:163], v[170:173], v[56:59]
	v_mfma_f32_16x16x32_bf16 v[48:51], v[146:149], v[178:181], v[48:51]
	v_mfma_f32_16x16x32_bf16 v[40:43], v[160:163], v[178:181], v[40:43]
	v_mfma_f32_16x16x32_bf16 v[32:35], v[146:149], v[186:189], v[32:35]
	v_mfma_f32_16x16x32_bf16 v[24:27], v[160:163], v[186:189], v[24:27]
	v_mfma_f32_16x16x32_bf16 v[16:19], v[146:149], v[194:197], v[16:19]
	v_mfma_f32_16x16x32_bf16 v[8:11], v[160:163], v[194:197], v[8:11]
	v_mfma_f32_16x16x32_bf16 v[60:63], v[150:153], v[174:177], v[60:63]
	v_mfma_f32_16x16x32_bf16 v[56:59], v[166:169], v[174:177], v[56:59]
	v_mfma_f32_16x16x32_bf16 v[48:51], v[150:153], v[182:185], v[48:51]
	v_mfma_f32_16x16x32_bf16 v[40:43], v[166:169], v[182:185], v[40:43]
	v_mfma_f32_16x16x32_bf16 v[32:35], v[150:153], v[190:193], v[32:35]
	v_mfma_f32_16x16x32_bf16 v[24:27], v[166:169], v[190:193], v[24:27]
	v_mfma_f32_16x16x32_bf16 v[16:19], v[150:153], v[202:205], v[16:19]
	v_mfma_f32_16x16x32_bf16 v[8:11], v[166:169], v[202:205], v[8:11]
	s_setprio 0
	s_barrier
	s_add_u32 s28, s34, 0x200000
	s_addc_u32 s29, s35, 0
	s_mov_b32 m0, s53
	s_nop 0
	global_load_lds_dwordx4 v130, s[28:29]
	s_mov_b32 m0, s54
	s_nop 0
	global_load_lds_dwordx4 v134, s[28:29]
	s_waitcnt vmcnt(6)
	s_barrier
; #define PG8_STAGE(bufoff, gbase, voff) do { _Pragma("unroll") for (int _i = 0; _i < 2; ++_i) \
;         __builtin_amdgcn_global_load_lds((const unsigned*)((const char*)(gbase) + (voff)[_i]), (LAS unsigned*)(lds + (bufoff) + ldsw + _i * 8192), 16, 0, 0); } while (0)
; #define PG8_LDA(dst, b, h) do { _Pragma("unroll") for (int m = 0; m < 4; ++m) _Pragma("unroll") for (int k = 0; k < 2; ++k) dst[m][k] = *(const LAS bf16x8*)(lds + PG8_SA(b, h) + aoff + m * 2048 + k * 1024); } while (0)
; #define PG8_LDB(dst, b, h) do { _Pragma("unroll") for (int n = 0; n < 2; ++n) _Pragma("unroll") for (int k = 0; k < 2; ++k) dst[n][k] = *(const LAS bf16x8*)(lds + PG8_SB(b, h) + boff + n * 2048 + k * 1024); } while (0)
; #define PG8_WAIT_V(n) asm volatile("s_waitcnt vmcnt(" #n ")" ::: "memory")
; #define PG8_WAIT_L(n) asm volatile("s_waitcnt lgkmcnt(" #n ")" ::: "memory")
; #define PG8_BAR __builtin_amdgcn_s_barrier()
; #define PG8_SCHED __builtin_amdgcn_sched_barrier(0)
; template <class Epi>
; __device__ __forceinline__ void gemm_phase(LAS unsigned char* lds, const bf16_t* A, int lda, const bf16_t* Bt, int ldb, int M, int N, int K, int asel, const Epi& E, const int fixed_round = -1) {
;     ...
;             PG8_WAIT_V(6); PG8_BAR; PG8_MMA(1, 1, At, B1); PG8_BAR;
;             PG8_LDB(B0, 1, 0); PG8_SCHED; PG8_LDA(At, 1, 0); PG8_STAGE(PG8_SA(0, 1), a2 + hstepA, voffA);
;             PG8_WAIT_L(8); PG8_BAR; PG8_WAIT_L(0); PG8_MMA(0, 0, At, B0); PG8_BAR; PG8_SCHED;
;             PG8_LDB(B1, 1, 1); PG8_STAGE(PG8_SB(1, 0), b3, voffB);
;             PG8_BAR; PG8_WAIT_L(0); PG8_MMA(0, 1, At, B1); PG8_BAR;
	s_setprio 1
	v_mfma_f32_16x16x32_bf16 v[52:55], v[206:209], v[170:173], v[52:55]
	v_mfma_f32_16x16x32_bf16 v[44:47], v[214:217], v[170:173], v[44:47]
	v_mfma_f32_16x16x32_bf16 v[36:39], v[206:209], v[178:181], v[36:39]
	v_mfma_f32_16x16x32_bf16 v[28:31], v[214:217], v[178:181], v[28:31]
	v_mfma_f32_16x16x32_bf16 v[20:23], v[206:209], v[186:189], v[20:23]
	v_mfma_f32_16x16x32_bf16 v[12:15], v[214:217], v[186:189], v[12:15]
	v_mfma_f32_16x16x32_bf16 v[4:7], v[206:209], v[194:197], v[4:7]
	v_mfma_f32_16x16x32_bf16 v[0:3], v[214:217], v[194:197], v[0:3]
	v_mfma_f32_16x16x32_bf16 v[52:55], v[210:213], v[174:177], v[52:55]
	v_mfma_f32_16x16x32_bf16 v[44:47], v[218:221], v[174:177], v[44:47]
	v_mfma_f32_16x16x32_bf16 v[36:39], v[210:213], v[182:185], v[36:39]
	v_mfma_f32_16x16x32_bf16 v[28:31], v[218:221], v[182:185], v[28:31]
	v_mfma_f32_16x16x32_bf16 v[20:23], v[210:213], v[190:193], v[20:23]
	v_mfma_f32_16x16x32_bf16 v[12:15], v[218:221], v[190:193], v[12:15]
	v_mfma_f32_16x16x32_bf16 v[4:7], v[210:213], v[202:205], v[4:7]
	v_mfma_f32_16x16x32_bf16 v[0:3], v[218:221], v[202:205], v[0:3]
	s_setprio 0
	s_barrier
	ds_read_b128 v[146:149], v143
	ds_read_b128 v[150:153], v143 offset:1024
	ds_read_b128 v[160:163], v143 offset:2048
	ds_read_b128 v[166:169], v143 offset:3072
	s_add_u32 s28, s36, 0x200000
	s_addc_u32 s29, s37, 0
	s_mov_b32 m0, s44
	ds_read_b128 v[170:173], v141 offset:32768
	ds_read_b128 v[174:177], v141 offset:33792
	ds_read_b128 v[178:181], v141 offset:34816
	ds_read_b128 v[182:185], v141 offset:35840
	ds_read_b128 v[186:189], v141 offset:36864
	ds_read_b128 v[190:193], v141 offset:37888
	ds_read_b128 v[194:197], v141 offset:38912
	ds_read_b128 v[202:205], v141 offset:39936
	global_load_lds_dwordx4 v128, s[28:29]
	s_mov_b32 m0, s45
	s_nop 0
	global_load_lds_dwordx4 v132, s[28:29]
	s_waitcnt lgkmcnt(8)
	s_barrier
	s_waitcnt lgkmcnt(0)
	s_setprio 1
	s_waitcnt lgkmcnt(0)
	v_mfma_f32_16x16x32_bf16 v[124:127], v[146:149], v[170:173], v[124:127]
	v_mfma_f32_16x16x32_bf16 v[120:123], v[160:163], v[170:173], v[120:123]
	v_mfma_f32_16x16x32_bf16 v[112:115], v[146:149], v[178:181], v[112:115]
	v_mfma_f32_16x16x32_bf16 v[104:107], v[160:163], v[178:181], v[104:107]
	v_mfma_f32_16x16x32_bf16 v[96:99], v[146:149], v[186:189], v[96:99]
	v_mfma_f32_16x16x32_bf16 v[88:91], v[160:163], v[186:189], v[88:91]
	v_mfma_f32_16x16x32_bf16 v[80:83], v[146:149], v[194:197], v[80:83]
	v_mfma_f32_16x16x32_bf16 v[72:75], v[160:163], v[194:197], v[72:75]
	v_mfma_f32_16x16x32_bf16 v[124:127], v[150:153], v[174:177], v[124:127]
	v_mfma_f32_16x16x32_bf16 v[120:123], v[166:169], v[174:177], v[120:123]
	v_mfma_f32_16x16x32_bf16 v[112:115], v[150:153], v[182:185], v[112:115]
	v_mfma_f32_16x16x32_bf16 v[104:107], v[166:169], v[182:185], v[104:107]
	v_mfma_f32_16x16x32_bf16 v[96:99], v[150:153], v[190:193], v[96:99]
	v_mfma_f32_16x16x32_bf16 v[88:91], v[166:169], v[190:193], v[88:91]
	v_mfma_f32_16x16x32_bf16 v[80:83], v[150:153], v[202:205], v[80:83]
	v_mfma_f32_16x16x32_bf16 v[72:75], v[166:169], v[202:205], v[72:75]
	s_setprio 0
	s_barrier
	s_mov_b32 m0, s55
	ds_read_b128 v[206:209], v144
	ds_read_b128 v[210:213], v144 offset:1024
	ds_read_b128 v[214:217], v144 offset:2048
	ds_read_b128 v[218:221], v144 offset:3072
	global_load_lds_dwordx4 v130, s[98:99]
	s_mov_b32 m0, s56
	s_nop 0
	global_load_lds_dwordx4 v134, s[98:99]
	s_barrier
; #define PG8_STAGE(bufoff, gbase, voff) do { _Pragma("unroll") for (int _i = 0; _i < 2; ++_i) \
;         __builtin_amdgcn_global_load_lds((const unsigned*)((const char*)(gbase) + (voff)[_i]), (LAS unsigned*)(lds + (bufoff) + ldsw + _i * 8192), 16, 0, 0); } while (0)
; #define PG8_LDA(dst, b, h) do { _Pragma("unroll") for (int m = 0; m < 4; ++m) _Pragma("unroll") for (int k = 0; k < 2; ++k) dst[m][k] = *(const LAS bf16x8*)(lds + PG8_SA(b, h) + aoff + m * 2048 + k * 1024); } while (0)
; #define PG8_WAIT_V(n) asm volatile("s_waitcnt vmcnt(" #n ")" ::: "memory")
; #define PG8_WAIT_L(n) asm volatile("s_waitcnt lgkmcnt(" #n ")" ::: "memory")
; #define PG8_BAR __builtin_amdgcn_s_barrier()
; #define PG8_SCHED __builtin_amdgcn_sched_barrier(0)
; template <class Epi>
; __device__ __forceinline__ void gemm_phase(LAS unsigned char* lds, const bf16_t* A, int lda, const bf16_t* Bt, int ldb, int M, int N, int K, int asel, const Epi& E, const int fixed_round = -1) {
;     ...
;             PG8_BAR; PG8_WAIT_L(0); PG8_MMA(0, 1, At, B1); PG8_BAR;
;             PG8_LDA(At, 1, 1); PG8_STAGE(PG8_SA(1, 0), a3, voffA);
;             PG8_BAR; PG8_WAIT_L(0); PG8_MMA(1, 0, At, B0); PG8_BAR; PG8_SCHED;
;             PG8_STAGE(PG8_SB(1, 1), b3 + hstepB, voffB);
;             PG8_WAIT_V(6); PG8_BAR; PG8_MMA(1, 1, At, B1); PG8_BAR;
;     ...
;     PG8_WAIT_V(0);
;     if (wr == 0) PG8_BAR;
;     PG8_BAR;
	s_waitcnt lgkmcnt(0)
	s_setprio 1
	s_waitcnt lgkmcnt(0)
	v_mfma_f32_16x16x32_bf16 v[116:119], v[206:209], v[170:173], v[116:119]
	v_mfma_f32_16x16x32_bf16 v[108:111], v[214:217], v[170:173], v[108:111]
	v_mfma_f32_16x16x32_bf16 v[100:103], v[206:209], v[178:181], v[100:103]
	v_mfma_f32_16x16x32_bf16 v[92:95], v[214:217], v[178:181], v[92:95]
	v_mfma_f32_16x16x32_bf16 v[84:87], v[206:209], v[186:189], v[84:87]
	v_mfma_f32_16x16x32_bf16 v[76:79], v[214:217], v[186:189], v[76:79]
	v_mfma_f32_16x16x32_bf16 v[68:71], v[206:209], v[194:197], v[68:71]
	v_mfma_f32_16x16x32_bf16 v[64:67], v[214:217], v[194:197], v[64:67]
	v_mfma_f32_16x16x32_bf16 v[116:119], v[210:213], v[174:177], v[116:119]
	v_mfma_f32_16x16x32_bf16 v[108:111], v[218:221], v[174:177], v[108:111]
	v_mfma_f32_16x16x32_bf16 v[100:103], v[210:213], v[182:185], v[100:103]
	v_mfma_f32_16x16x32_bf16 v[92:95], v[218:221], v[182:185], v[92:95]
	v_mfma_f32_16x16x32_bf16 v[84:87], v[210:213], v[190:193], v[84:87]
	v_mfma_f32_16x16x32_bf16 v[76:79], v[218:221], v[190:193], v[76:79]
	v_mfma_f32_16x16x32_bf16 v[68:71], v[210:213], v[202:205], v[68:71]
	v_mfma_f32_16x16x32_bf16 v[64:67], v[218:221], v[202:205], v[64:67]
	s_setprio 0
	s_mov_b32 m0, s46
	s_barrier
	ds_read_b128 v[170:173], v141 offset:49152
	ds_read_b128 v[174:177], v141 offset:50176
	ds_read_b128 v[178:181], v141 offset:51200
	ds_read_b128 v[182:185], v141 offset:52224
	ds_read_b128 v[186:189], v141 offset:53248
	ds_read_b128 v[190:193], v141 offset:54272
	ds_read_b128 v[194:197], v141 offset:55296
	ds_read_b128 v[202:205], v141 offset:56320
	global_load_lds_dwordx4 v128, s[100:101]
	s_mov_b32 m0, s47
	s_nop 0
	global_load_lds_dwordx4 v132, s[100:101]
	s_barrier
	s_waitcnt lgkmcnt(0)
	s_setprio 1
	s_waitcnt lgkmcnt(0)
	v_mfma_f32_16x16x32_bf16 v[60:63], v[146:149], v[170:173], v[60:63]
	v_mfma_f32_16x16x32_bf16 v[56:59], v[160:163], v[170:173], v[56:59]
	v_mfma_f32_16x16x32_bf16 v[48:51], v[146:149], v[178:181], v[48:51]
	v_mfma_f32_16x16x32_bf16 v[40:43], v[160:163], v[178:181], v[40:43]
	v_mfma_f32_16x16x32_bf16 v[32:35], v[146:149], v[186:189], v[32:35]
	v_mfma_f32_16x16x32_bf16 v[24:27], v[160:163], v[186:189], v[24:27]
	v_mfma_f32_16x16x32_bf16 v[16:19], v[146:149], v[194:197], v[16:19]
	v_mfma_f32_16x16x32_bf16 v[8:11], v[160:163], v[194:197], v[8:11]
	v_mfma_f32_16x16x32_bf16 v[60:63], v[150:153], v[174:177], v[60:63]
	v_mfma_f32_16x16x32_bf16 v[56:59], v[166:169], v[174:177], v[56:59]
	v_mfma_f32_16x16x32_bf16 v[48:51], v[150:153], v[182:185], v[48:51]
	v_mfma_f32_16x16x32_bf16 v[40:43], v[166:169], v[182:185], v[40:43]
	v_mfma_f32_16x16x32_bf16 v[32:35], v[150:153], v[190:193], v[32:35]
	v_mfma_f32_16x16x32_bf16 v[24:27], v[166:169], v[190:193], v[24:27]
	v_mfma_f32_16x16x32_bf16 v[16:19], v[150:153], v[202:205], v[16:19]
	v_mfma_f32_16x16x32_bf16 v[8:11], v[166:169], v[202:205], v[8:11]
	s_setprio 0
	s_barrier
	s_add_u32 s28, s34, 0x200080
	s_addc_u32 s29, s35, 0
	s_mov_b32 m0, s57
	s_nop 0
	global_load_lds_dwordx4 v130, s[28:29]
	s_mov_b32 m0, s58
	s_nop 0
	global_load_lds_dwordx4 v134, s[28:29]
	s_waitcnt vmcnt(6)
	s_barrier
	s_setprio 1
	v_mfma_f32_16x16x32_bf16 v[52:55], v[206:209], v[170:173], v[52:55]
	v_mfma_f32_16x16x32_bf16 v[44:47], v[214:217], v[170:173], v[44:47]
	v_mfma_f32_16x16x32_bf16 v[36:39], v[206:209], v[178:181], v[36:39]
	v_mfma_f32_16x16x32_bf16 v[28:31], v[214:217], v[178:181], v[28:31]
	v_mfma_f32_16x16x32_bf16 v[20:23], v[206:209], v[186:189], v[20:23]
	v_mfma_f32_16x16x32_bf16 v[12:15], v[214:217], v[186:189], v[12:15]
	v_mfma_f32_16x16x32_bf16 v[4:7], v[206:209], v[194:197], v[4:7]
	v_mfma_f32_16x16x32_bf16 v[0:3], v[214:217], v[194:197], v[0:3]
	v_mfma_f32_16x16x32_bf16 v[52:55], v[210:213], v[174:177], v[52:55]
	v_mfma_f32_16x16x32_bf16 v[44:47], v[218:221], v[174:177], v[44:47]
	v_mfma_f32_16x16x32_bf16 v[36:39], v[210:213], v[182:185], v[36:39]
	v_mfma_f32_16x16x32_bf16 v[28:31], v[218:221], v[182:185], v[28:31]
	v_mfma_f32_16x16x32_bf16 v[20:23], v[210:213], v[190:193], v[20:23]
	v_mfma_f32_16x16x32_bf16 v[12:15], v[218:221], v[190:193], v[12:15]
	v_mfma_f32_16x16x32_bf16 v[4:7], v[210:213], v[202:205], v[4:7]
	v_mfma_f32_16x16x32_bf16 v[0:3], v[218:221], v[202:205], v[0:3]
	s_setprio 0
	s_add_i32 s48, s48, 2
	s_add_u32 s20, s20, 0x100
	s_addc_u32 s21, s21, 0
	s_cmpk_lt_u32 s48, 0x7e
	s_cbranch_scc1 .Lrot_5
	s_barrier
	s_waitcnt vmcnt(0)
	v_writelane_b32 v255, s8, 26
	s_cmpk_gt_u32 s41, 0xff
	s_nop 0
	v_writelane_b32 v255, s9, 27
	s_cbranch_scc1 .LBB0_654
	s_barrier

; #define PG8_STAGE(bufoff, gbase, voff) do { _Pragma("unroll") for (int _i = 0; _i < 2; ++_i) \
;         __builtin_amdgcn_global_load_lds((const unsigned*)((const char*)(gbase) + (voff)[_i]), (LAS unsigned*)(lds + (bufoff) + ldsw + _i * 8192), 16, 0, 0); } while (0)
; #define PG8_LDA(dst, b, h) do { _Pragma("unroll") for (int m = 0; m < 4; ++m) _Pragma("unroll") for (int k = 0; k < 2; ++k) dst[m][k] = *(const LAS bf16x8*)(lds + PG8_SA(b, h) + aoff + m * 2048 + k * 1024); } while (0)
; #define PG8_LDB(dst, b, h) do { _Pragma("unroll") for (int n = 0; n < 2; ++n) _Pragma("unroll") for (int k = 0; k < 2; ++k) dst[n][k] = *(const LAS bf16x8*)(lds + PG8_SB(b, h) + boff + n * 2048 + k * 1024); } while (0)
; #define PG8_WAIT_V(n) asm volatile("s_waitcnt vmcnt(" #n ")" ::: "memory")
; #define PG8_WAIT_L(n) asm volatile("s_waitcnt lgkmcnt(" #n ")" ::: "memory")
; #define PG8_BAR __builtin_amdgcn_s_barrier()
; #define PG8_SCHED __builtin_amdgcn_sched_barrier(0)
; template <class Epi>
; __device__ __forceinline__ void gemm_phase(LAS unsigned char* lds, const bf16_t* A, int lda, const bf16_t* Bt, int ldb, int M, int N, int K, int asel, const Epi& E, const int fixed_round = -1) {
;     ...
;         const char* nA = has_next ? PG8_ABASE(nxt) : cA; const char* nB = has_next ? (const char*)Bt + (size_t)nxt.pn * tstepB : cB;
;         for (int t = 0; t < nt; t += 2) {
;             const bool last = (t == nt - 2);
;             const char* a1 = cA + (size_t)(t + 1) * kstep;
;             const char* a2 = last ? nA : cA + (size_t)(t + 2) * kstep; const char* b2 = last ? nB : cB + (size_t)(t + 2) * kstep;
;             const char* a3 = a2 + kstep; const char* b3 = b2 + kstep;
;             PG8_LDB(B0, 0, 0); PG8_SCHED; PG8_LDA(At, 0, 0); PG8_STAGE(PG8_SA(1, 1), a1 + hstepA, voffA);
;             PG8_WAIT_L(8); PG8_BAR; PG8_WAIT_L(0); PG8_MMA(0, 0, At, B0); PG8_BAR; PG8_SCHED;
;             PG8_LDB(B1, 0, 1); PG8_STAGE(PG8_SB(0, 0), b2, voffB);
;             PG8_BAR; PG8_WAIT_L(0); PG8_MMA(0, 1, At, B1); PG8_BAR;
;             PG8_LDA(At, 0, 1); PG8_STAGE(PG8_SA(0, 0), a2, voffA);
;             PG8_BAR; PG8_WAIT_L(0); PG8_MMA(1, 0, At, B0); PG8_BAR; PG8_SCHED;
;             PG8_STAGE(PG8_SB(0, 1), b2 + hstepB, voffB);
;             PG8_WAIT_V(6); PG8_BAR; PG8_MMA(1, 1, At, B1); PG8_BAR;
.LBB0_690:
	ds_read_b128 v[146:149], v138
	ds_read_b128 v[150:153], v138 offset:1024
	ds_read_b128 v[160:163], v138 offset:2048
	ds_read_b128 v[166:169], v138 offset:3072
	s_mov_b32 m0, s59
	v_lshl_add_u64 v[156:157], v[134:135], 0, s[4:5]
	ds_read_b128 v[170:173], v139
	ds_read_b128 v[174:177], v139 offset:1024
	ds_read_b128 v[178:181], v139 offset:2048
	ds_read_b128 v[182:185], v139 offset:3072
	ds_read_b128 v[186:189], v139 offset:4096
	ds_read_b128 v[190:193], v139 offset:5120
	ds_read_b128 v[194:197], v139 offset:6144
	ds_read_b128 v[202:205], v139 offset:7168
	global_load_lds_dwordx4 v[156:157], off
	v_lshl_add_u64 v[156:157], v[136:137], 0, s[4:5]
	s_mov_b32 m0, s60
	s_nop 0
	global_load_lds_dwordx4 v[156:157], off
	s_waitcnt lgkmcnt(8)
	s_barrier
	s_waitcnt lgkmcnt(0)
	s_setprio 1
	s_waitcnt lgkmcnt(0)
	v_mfma_f32_16x16x32_bf16 v[124:127], v[146:149], v[170:173], v[124:127]
	v_mfma_f32_16x16x32_bf16 v[120:123], v[160:163], v[170:173], v[120:123]
	v_mfma_f32_16x16x32_bf16 v[112:115], v[146:149], v[178:181], v[112:115]
	v_mfma_f32_16x16x32_bf16 v[104:107], v[160:163], v[178:181], v[104:107]
	v_mfma_f32_16x16x32_bf16 v[96:99], v[146:149], v[186:189], v[96:99]
	v_mfma_f32_16x16x32_bf16 v[88:91], v[160:163], v[186:189], v[88:91]
	v_mfma_f32_16x16x32_bf16 v[80:83], v[146:149], v[194:197], v[80:83]
	v_mfma_f32_16x16x32_bf16 v[72:75], v[160:163], v[194:197], v[72:75]
	v_mfma_f32_16x16x32_bf16 v[124:127], v[150:153], v[174:177], v[124:127]
	v_mfma_f32_16x16x32_bf16 v[120:123], v[166:169], v[174:177], v[120:123]
	v_mfma_f32_16x16x32_bf16 v[112:115], v[150:153], v[182:185], v[112:115]
	v_mfma_f32_16x16x32_bf16 v[104:107], v[166:169], v[182:185], v[104:107]
	v_mfma_f32_16x16x32_bf16 v[96:99], v[150:153], v[190:193], v[96:99]
	v_mfma_f32_16x16x32_bf16 v[88:91], v[166:169], v[190:193], v[88:91]
	v_mfma_f32_16x16x32_bf16 v[80:83], v[150:153], v[202:205], v[80:83]
	v_mfma_f32_16x16x32_bf16 v[72:75], v[166:169], v[202:205], v[72:75]
	s_setprio 0
	s_barrier
	s_add_u32 s6, s4, 0xe7900080
	s_addc_u32 s7, s5, -1
	s_cmpk_lg_i32 s58, 0x7c
	s_cselect_b32 s6, s6, 0
	s_cselect_b32 s7, s7, 0
	s_add_u32 s40, s8, s6
	s_addc_u32 s41, s9, s7
	s_add_u32 s6, s2, s6
	s_addc_u32 s7, s3, s7
	s_mov_b32 m0, s61
	s_add_u32 s98, s6, s0
	s_addc_u32 s99, s7, s1
	ds_read_b128 v[206:209], v140
	ds_read_b128 v[210:213], v140 offset:1024
	ds_read_b128 v[214:217], v140 offset:2048
	ds_read_b128 v[218:221], v140 offset:3072
	global_load_lds_dwordx4 v144, s[6:7]
	s_mov_b32 m0, s62
	s_nop 0
	global_load_lds_dwordx4 v132, s[6:7]
	s_barrier
	s_waitcnt lgkmcnt(0)
	s_setprio 1
	s_waitcnt lgkmcnt(0)
	v_mfma_f32_16x16x32_bf16 v[116:119], v[206:209], v[170:173], v[116:119]
	v_mfma_f32_16x16x32_bf16 v[108:111], v[214:217], v[170:173], v[108:111]
	v_mfma_f32_16x16x32_bf16 v[100:103], v[206:209], v[178:181], v[100:103]
	v_mfma_f32_16x16x32_bf16 v[92:95], v[214:217], v[178:181], v[92:95]
	v_mfma_f32_16x16x32_bf16 v[84:87], v[206:209], v[186:189], v[84:87]
	v_mfma_f32_16x16x32_bf16 v[76:79], v[214:217], v[186:189], v[76:79]
	v_mfma_f32_16x16x32_bf16 v[68:71], v[206:209], v[194:197], v[68:71]
	v_mfma_f32_16x16x32_bf16 v[64:67], v[214:217], v[194:197], v[64:67]
	v_mfma_f32_16x16x32_bf16 v[116:119], v[210:213], v[174:177], v[116:119]
	v_mfma_f32_16x16x32_bf16 v[108:111], v[218:221], v[174:177], v[108:111]
	v_mfma_f32_16x16x32_bf16 v[100:103], v[210:213], v[182:185], v[100:103]
	v_mfma_f32_16x16x32_bf16 v[92:95], v[218:221], v[182:185], v[92:95]
	v_mfma_f32_16x16x32_bf16 v[84:87], v[210:213], v[190:193], v[84:87]
	v_mfma_f32_16x16x32_bf16 v[76:79], v[218:221], v[190:193], v[76:79]
	v_mfma_f32_16x16x32_bf16 v[68:71], v[210:213], v[202:205], v[68:71]
	v_mfma_f32_16x16x32_bf16 v[64:67], v[218:221], v[202:205], v[64:67]
	s_setprio 0
	s_mov_b32 m0, s52
	s_add_u32 s100, s40, s0
	s_addc_u32 s101, s41, s1
	s_barrier
	ds_read_b128 v[170:173], v139 offset:16384
	ds_read_b128 v[174:177], v139 offset:17408
	ds_read_b128 v[178:181], v139 offset:18432
	ds_read_b128 v[182:185], v139 offset:19456
	ds_read_b128 v[186:189], v139 offset:20480
	ds_read_b128 v[190:193], v139 offset:21504
	ds_read_b128 v[194:197], v139 offset:22528
	ds_read_b128 v[202:205], v139 offset:23552
	global_load_lds_dwordx4 v128, s[40:41]
	s_mov_b32 m0, s53
	s_nop 0
	global_load_lds_dwordx4 v130, s[40:41]
	s_barrier
	s_waitcnt lgkmcnt(0)
	s_setprio 1
	s_waitcnt lgkmcnt(0)
	v_mfma_f32_16x16x32_bf16 v[60:63], v[146:149], v[170:173], v[60:63]
	v_mfma_f32_16x16x32_bf16 v[56:59], v[160:163], v[170:173], v[56:59]
	v_mfma_f32_16x16x32_bf16 v[48:51], v[146:149], v[178:181], v[48:51]
	v_mfma_f32_16x16x32_bf16 v[40:43], v[160:163], v[178:181], v[40:43]
	v_mfma_f32_16x16x32_bf16 v[32:35], v[146:149], v[186:189], v[32:35]
	v_mfma_f32_16x16x32_bf16 v[24:27], v[160:163], v[186:189], v[24:27]
	v_mfma_f32_16x16x32_bf16 v[16:19], v[146:149], v[194:197], v[16:19]
	v_mfma_f32_16x16x32_bf16 v[8:11], v[160:163], v[194:197], v[8:11]
	v_mfma_f32_16x16x32_bf16 v[60:63], v[150:153], v[174:177], v[60:63]
	v_mfma_f32_16x16x32_bf16 v[56:59], v[166:169], v[174:177], v[56:59]
	v_mfma_f32_16x16x32_bf16 v[48:51], v[150:153], v[182:185], v[48:51]
	v_mfma_f32_16x16x32_bf16 v[40:43], v[166:169], v[182:185], v[40:43]
	v_mfma_f32_16x16x32_bf16 v[32:35], v[150:153], v[190:193], v[32:35]
	v_mfma_f32_16x16x32_bf16 v[24:27], v[166:169], v[190:193], v[24:27]
	v_mfma_f32_16x16x32_bf16 v[16:19], v[150:153], v[202:205], v[16:19]
	v_mfma_f32_16x16x32_bf16 v[8:11], v[166:169], v[202:205], v[8:11]
	s_setprio 0
	s_barrier
	s_add_u32 s28, s6, 0x200000
	s_addc_u32 s29, s7, 0
	s_mov_b32 m0, s63
	s_nop 0
	global_load_lds_dwordx4 v144, s[28:29]
	s_mov_b32 m0, s64
	s_nop 0
	global_load_lds_dwordx4 v132, s[28:29]
	s_waitcnt vmcnt(6)
	s_barrier
; #define PG8_STAGE(bufoff, gbase, voff) do { _Pragma("unroll") for (int _i = 0; _i < 2; ++_i) \
;         __builtin_amdgcn_global_load_lds((const unsigned*)((const char*)(gbase) + (voff)[_i]), (LAS unsigned*)(lds + (bufoff) + ldsw + _i * 8192), 16, 0, 0); } while (0)
; #define PG8_LDA(dst, b, h) do { _Pragma("unroll") for (int m = 0; m < 4; ++m) _Pragma("unroll") for (int k = 0; k < 2; ++k) dst[m][k] = *(const LAS bf16x8*)(lds + PG8_SA(b, h) + aoff + m * 2048 + k * 1024); } while (0)
; #define PG8_LDB(dst, b, h) do { _Pragma("unroll") for (int n = 0; n < 2; ++n) _Pragma("unroll") for (int k = 0; k < 2; ++k) dst[n][k] = *(const LAS bf16x8*)(lds + PG8_SB(b, h) + boff + n * 2048 + k * 1024); } while (0)
; #define PG8_WAIT_V(n) asm volatile("s_waitcnt vmcnt(" #n ")" ::: "memory")
; #define PG8_WAIT_L(n) asm volatile("s_waitcnt lgkmcnt(" #n ")" ::: "memory")
; #define PG8_BAR __builtin_amdgcn_s_barrier()
; #define PG8_SCHED __builtin_amdgcn_sched_barrier(0)
; template <class Epi>
; __device__ __forceinline__ void gemm_phase(LAS unsigned char* lds, const bf16_t* A, int lda, const bf16_t* Bt, int ldb, int M, int N, int K, int asel, const Epi& E, const int fixed_round = -1) {
;     ...
;             PG8_WAIT_V(6); PG8_BAR; PG8_MMA(1, 1, At, B1); PG8_BAR;
;             PG8_LDB(B0, 1, 0); PG8_SCHED; PG8_LDA(At, 1, 0); PG8_STAGE(PG8_SA(0, 1), a2 + hstepA, voffA);
;             PG8_WAIT_L(8); PG8_BAR; PG8_WAIT_L(0); PG8_MMA(0, 0, At, B0); PG8_BAR; PG8_SCHED;
;             PG8_LDB(B1, 1, 1); PG8_STAGE(PG8_SB(1, 0), b3, voffB);
;             PG8_BAR; PG8_WAIT_L(0); PG8_MMA(0, 1, At, B1); PG8_BAR;
	s_setprio 1
	v_mfma_f32_16x16x32_bf16 v[52:55], v[206:209], v[170:173], v[52:55]
	v_mfma_f32_16x16x32_bf16 v[44:47], v[214:217], v[170:173], v[44:47]
	v_mfma_f32_16x16x32_bf16 v[36:39], v[206:209], v[178:181], v[36:39]
	v_mfma_f32_16x16x32_bf16 v[28:31], v[214:217], v[178:181], v[28:31]
	v_mfma_f32_16x16x32_bf16 v[20:23], v[206:209], v[186:189], v[20:23]
	v_mfma_f32_16x16x32_bf16 v[12:15], v[214:217], v[186:189], v[12:15]
	v_mfma_f32_16x16x32_bf16 v[4:7], v[206:209], v[194:197], v[4:7]
	v_mfma_f32_16x16x32_bf16 v[0:3], v[214:217], v[194:197], v[0:3]
	v_mfma_f32_16x16x32_bf16 v[52:55], v[210:213], v[174:177], v[52:55]
	v_mfma_f32_16x16x32_bf16 v[44:47], v[218:221], v[174:177], v[44:47]
	v_mfma_f32_16x16x32_bf16 v[36:39], v[210:213], v[182:185], v[36:39]
	v_mfma_f32_16x16x32_bf16 v[28:31], v[218:221], v[182:185], v[28:31]
	v_mfma_f32_16x16x32_bf16 v[20:23], v[210:213], v[190:193], v[20:23]
	v_mfma_f32_16x16x32_bf16 v[12:15], v[218:221], v[190:193], v[12:15]
	v_mfma_f32_16x16x32_bf16 v[4:7], v[210:213], v[202:205], v[4:7]
	v_mfma_f32_16x16x32_bf16 v[0:3], v[218:221], v[202:205], v[0:3]
	s_setprio 0
	s_barrier
	ds_read_b128 v[146:149], v141
	ds_read_b128 v[150:153], v141 offset:1024
	ds_read_b128 v[160:163], v141 offset:2048
	ds_read_b128 v[166:169], v141 offset:3072
	s_add_u32 s28, s40, 0x200000
	s_addc_u32 s29, s41, 0
	s_mov_b32 m0, s54
	ds_read_b128 v[170:173], v139 offset:32768
	ds_read_b128 v[174:177], v139 offset:33792
	ds_read_b128 v[178:181], v139 offset:34816
	ds_read_b128 v[182:185], v139 offset:35840
	ds_read_b128 v[186:189], v139 offset:36864
	ds_read_b128 v[190:193], v139 offset:37888
	ds_read_b128 v[194:197], v139 offset:38912
	ds_read_b128 v[202:205], v139 offset:39936
	global_load_lds_dwordx4 v128, s[28:29]
	s_mov_b32 m0, s55
	s_nop 0
	global_load_lds_dwordx4 v130, s[28:29]
	s_waitcnt lgkmcnt(8)
	s_barrier
	s_waitcnt lgkmcnt(0)
	s_setprio 1
	s_waitcnt lgkmcnt(0)
	v_mfma_f32_16x16x32_bf16 v[124:127], v[146:149], v[170:173], v[124:127]
	v_mfma_f32_16x16x32_bf16 v[120:123], v[160:163], v[170:173], v[120:123]
	v_mfma_f32_16x16x32_bf16 v[112:115], v[146:149], v[178:181], v[112:115]
	v_mfma_f32_16x16x32_bf16 v[104:107], v[160:163], v[178:181], v[104:107]
	v_mfma_f32_16x16x32_bf16 v[96:99], v[146:149], v[186:189], v[96:99]
	v_mfma_f32_16x16x32_bf16 v[88:91], v[160:163], v[186:189], v[88:91]
	v_mfma_f32_16x16x32_bf16 v[80:83], v[146:149], v[194:197], v[80:83]
	v_mfma_f32_16x16x32_bf16 v[72:75], v[160:163], v[194:197], v[72:75]
	v_mfma_f32_16x16x32_bf16 v[124:127], v[150:153], v[174:177], v[124:127]
	v_mfma_f32_16x16x32_bf16 v[120:123], v[166:169], v[174:177], v[120:123]
	v_mfma_f32_16x16x32_bf16 v[112:115], v[150:153], v[182:185], v[112:115]
	v_mfma_f32_16x16x32_bf16 v[104:107], v[166:169], v[182:185], v[104:107]
	v_mfma_f32_16x16x32_bf16 v[96:99], v[150:153], v[190:193], v[96:99]
	v_mfma_f32_16x16x32_bf16 v[88:91], v[166:169], v[190:193], v[88:91]
	v_mfma_f32_16x16x32_bf16 v[80:83], v[150:153], v[202:205], v[80:83]
	v_mfma_f32_16x16x32_bf16 v[72:75], v[166:169], v[202:205], v[72:75]
	s_setprio 0
	s_barrier
	s_mov_b32 m0, s65
	ds_read_b128 v[206:209], v142
	ds_read_b128 v[210:213], v142 offset:1024
	ds_read_b128 v[214:217], v142 offset:2048
	ds_read_b128 v[218:221], v142 offset:3072
	global_load_lds_dwordx4 v144, s[98:99]
	s_mov_b32 m0, s66
	s_nop 0
	global_load_lds_dwordx4 v132, s[98:99]
	s_barrier
; #define PG8_STAGE(bufoff, gbase, voff) do { _Pragma("unroll") for (int _i = 0; _i < 2; ++_i) \
;         __builtin_amdgcn_global_load_lds((const unsigned*)((const char*)(gbase) + (voff)[_i]), (LAS unsigned*)(lds + (bufoff) + ldsw + _i * 8192), 16, 0, 0); } while (0)
; #define PG8_LDA(dst, b, h) do { _Pragma("unroll") for (int m = 0; m < 4; ++m) _Pragma("unroll") for (int k = 0; k < 2; ++k) dst[m][k] = *(const LAS bf16x8*)(lds + PG8_SA(b, h) + aoff + m * 2048 + k * 1024); } while (0)
; #define PG8_WAIT_V(n) asm volatile("s_waitcnt vmcnt(" #n ")" ::: "memory")
; #define PG8_WAIT_L(n) asm volatile("s_waitcnt lgkmcnt(" #n ")" ::: "memory")
; #define PG8_BAR __builtin_amdgcn_s_barrier()
; #define PG8_SCHED __builtin_amdgcn_sched_barrier(0)
; template <class Epi>
; __device__ __forceinline__ void gemm_phase(LAS unsigned char* lds, const bf16_t* A, int lda, const bf16_t* Bt, int ldb, int M, int N, int K, int asel, const Epi& E, const int fixed_round = -1) {
;     ...
;             PG8_BAR; PG8_WAIT_L(0); PG8_MMA(0, 1, At, B1); PG8_BAR;
;             PG8_LDA(At, 1, 1); PG8_STAGE(PG8_SA(1, 0), a3, voffA);
;             PG8_BAR; PG8_WAIT_L(0); PG8_MMA(1, 0, At, B0); PG8_BAR; PG8_SCHED;
;             PG8_STAGE(PG8_SB(1, 1), b3 + hstepB, voffB);
;             PG8_WAIT_V(6); PG8_BAR; PG8_MMA(1, 1, At, B1); PG8_BAR;
;     ...
;     PG8_WAIT_V(0);
;     if (wr == 0) PG8_BAR;
;     PG8_BAR;
	s_waitcnt lgkmcnt(0)
	s_setprio 1
	s_waitcnt lgkmcnt(0)
	v_mfma_f32_16x16x32_bf16 v[116:119], v[206:209], v[170:173], v[116:119]
	v_mfma_f32_16x16x32_bf16 v[108:111], v[214:217], v[170:173], v[108:111]
	v_mfma_f32_16x16x32_bf16 v[100:103], v[206:209], v[178:181], v[100:103]
	v_mfma_f32_16x16x32_bf16 v[92:95], v[214:217], v[178:181], v[92:95]
	v_mfma_f32_16x16x32_bf16 v[84:87], v[206:209], v[186:189], v[84:87]
	v_mfma_f32_16x16x32_bf16 v[76:79], v[214:217], v[186:189], v[76:79]
	v_mfma_f32_16x16x32_bf16 v[68:71], v[206:209], v[194:197], v[68:71]
	v_mfma_f32_16x16x32_bf16 v[64:67], v[214:217], v[194:197], v[64:67]
	v_mfma_f32_16x16x32_bf16 v[116:119], v[210:213], v[174:177], v[116:119]
	v_mfma_f32_16x16x32_bf16 v[108:111], v[218:221], v[174:177], v[108:111]
	v_mfma_f32_16x16x32_bf16 v[100:103], v[210:213], v[182:185], v[100:103]
	v_mfma_f32_16x16x32_bf16 v[92:95], v[218:221], v[182:185], v[92:95]
	v_mfma_f32_16x16x32_bf16 v[84:87], v[210:213], v[190:193], v[84:87]
	v_mfma_f32_16x16x32_bf16 v[76:79], v[218:221], v[190:193], v[76:79]
	v_mfma_f32_16x16x32_bf16 v[68:71], v[210:213], v[202:205], v[68:71]
	v_mfma_f32_16x16x32_bf16 v[64:67], v[218:221], v[202:205], v[64:67]
	s_setprio 0
	s_mov_b32 m0, s56
	s_barrier
	ds_read_b128 v[170:173], v139 offset:49152
	ds_read_b128 v[174:177], v139 offset:50176
	ds_read_b128 v[178:181], v139 offset:51200
	ds_read_b128 v[182:185], v139 offset:52224
	ds_read_b128 v[186:189], v139 offset:53248
	ds_read_b128 v[190:193], v139 offset:54272
	ds_read_b128 v[194:197], v139 offset:55296
	ds_read_b128 v[202:205], v139 offset:56320
	global_load_lds_dwordx4 v128, s[100:101]
	s_mov_b32 m0, s57
	s_nop 0
	global_load_lds_dwordx4 v130, s[100:101]
	s_barrier
	s_waitcnt lgkmcnt(0)
	s_setprio 1
	s_waitcnt lgkmcnt(0)
	v_mfma_f32_16x16x32_bf16 v[60:63], v[146:149], v[170:173], v[60:63]
	v_mfma_f32_16x16x32_bf16 v[56:59], v[160:163], v[170:173], v[56:59]
	v_mfma_f32_16x16x32_bf16 v[48:51], v[146:149], v[178:181], v[48:51]
	v_mfma_f32_16x16x32_bf16 v[40:43], v[160:163], v[178:181], v[40:43]
	v_mfma_f32_16x16x32_bf16 v[32:35], v[146:149], v[186:189], v[32:35]
	v_mfma_f32_16x16x32_bf16 v[24:27], v[160:163], v[186:189], v[24:27]
	v_mfma_f32_16x16x32_bf16 v[16:19], v[146:149], v[194:197], v[16:19]
	v_mfma_f32_16x16x32_bf16 v[8:11], v[160:163], v[194:197], v[8:11]
	v_mfma_f32_16x16x32_bf16 v[60:63], v[150:153], v[174:177], v[60:63]
	v_mfma_f32_16x16x32_bf16 v[56:59], v[166:169], v[174:177], v[56:59]
	v_mfma_f32_16x16x32_bf16 v[48:51], v[150:153], v[182:185], v[48:51]
	v_mfma_f32_16x16x32_bf16 v[40:43], v[166:169], v[182:185], v[40:43]
	v_mfma_f32_16x16x32_bf16 v[32:35], v[150:153], v[190:193], v[32:35]
	v_mfma_f32_16x16x32_bf16 v[24:27], v[166:169], v[190:193], v[24:27]
	v_mfma_f32_16x16x32_bf16 v[16:19], v[150:153], v[202:205], v[16:19]
	v_mfma_f32_16x16x32_bf16 v[8:11], v[166:169], v[202:205], v[8:11]
	s_setprio 0
	s_barrier
	s_add_u32 s6, s6, 0x200080
	s_addc_u32 s7, s7, 0
	s_mov_b32 m0, s67
	s_nop 0
	global_load_lds_dwordx4 v144, s[6:7]
	s_mov_b32 m0, s68
	s_nop 0
	global_load_lds_dwordx4 v132, s[6:7]
	s_waitcnt vmcnt(6)
	s_barrier
	s_setprio 1
	v_mfma_f32_16x16x32_bf16 v[52:55], v[206:209], v[170:173], v[52:55]
	v_mfma_f32_16x16x32_bf16 v[44:47], v[214:217], v[170:173], v[44:47]
	v_mfma_f32_16x16x32_bf16 v[36:39], v[206:209], v[178:181], v[36:39]
	v_mfma_f32_16x16x32_bf16 v[28:31], v[214:217], v[178:181], v[28:31]
	v_mfma_f32_16x16x32_bf16 v[20:23], v[206:209], v[186:189], v[20:23]
	v_mfma_f32_16x16x32_bf16 v[12:15], v[214:217], v[186:189], v[12:15]
	v_mfma_f32_16x16x32_bf16 v[4:7], v[206:209], v[194:197], v[4:7]
	v_mfma_f32_16x16x32_bf16 v[0:3], v[214:217], v[194:197], v[0:3]
	v_mfma_f32_16x16x32_bf16 v[52:55], v[210:213], v[174:177], v[52:55]
	v_mfma_f32_16x16x32_bf16 v[44:47], v[218:221], v[174:177], v[44:47]
	v_mfma_f32_16x16x32_bf16 v[36:39], v[210:213], v[182:185], v[36:39]
	v_mfma_f32_16x16x32_bf16 v[28:31], v[218:221], v[182:185], v[28:31]
	v_mfma_f32_16x16x32_bf16 v[20:23], v[210:213], v[190:193], v[20:23]
	v_mfma_f32_16x16x32_bf16 v[12:15], v[218:221], v[190:193], v[12:15]
	v_mfma_f32_16x16x32_bf16 v[4:7], v[210:213], v[202:205], v[4:7]
	v_mfma_f32_16x16x32_bf16 v[0:3], v[218:221], v[202:205], v[0:3]
	s_setprio 0
	s_add_i32 s58, s58, 2
	s_add_u32 s4, s4, 0x100
	s_addc_u32 s5, s5, 0
	s_cmpk_lt_u32 s58, 0x7e
	s_cbranch_scc1 .Lrot_6
	s_barrier
	s_waitcnt vmcnt(0)
	s_cmpk_gt_u32 s51, 0xff
	s_cbranch_scc1 .LBB0_693
	s_barrier

; #define PG8_STAGE(bufoff, gbase, voff) do { _Pragma("unroll") for (int _i = 0; _i < 2; ++_i) \
;         __builtin_amdgcn_global_load_lds((const unsigned*)((const char*)(gbase) + (voff)[_i]), (LAS unsigned*)(lds + (bufoff) + ldsw + _i * 8192), 16, 0, 0); } while (0)
; #define PG8_LDA(dst, b, h) do { _Pragma("unroll") for (int m = 0; m < 4; ++m) _Pragma("unroll") for (int k = 0; k < 2; ++k) dst[m][k] = *(const LAS bf16x8*)(lds + PG8_SA(b, h) + aoff + m * 2048 + k * 1024); } while (0)
; #define PG8_LDB(dst, b, h) do { _Pragma("unroll") for (int n = 0; n < 2; ++n) _Pragma("unroll") for (int k = 0; k < 2; ++k) dst[n][k] = *(const LAS bf16x8*)(lds + PG8_SB(b, h) + boff + n * 2048 + k * 1024); } while (0)
; #define PG8_WAIT_V(n) asm volatile("s_waitcnt vmcnt(" #n ")" ::: "memory")
; #define PG8_WAIT_L(n) asm volatile("s_waitcnt lgkmcnt(" #n ")" ::: "memory")
; #define PG8_BAR __builtin_amdgcn_s_barrier()
; #define PG8_SCHED __builtin_amdgcn_sched_barrier(0)
; template <class Epi>
; __device__ __forceinline__ void gemm_phase(LAS unsigned char* lds, const bf16_t* A, int lda, const bf16_t* Bt, int ldb, int M, int N, int K, int asel, const Epi& E, const int fixed_round = -1) {
;     ...
;         const char* nA = has_next ? PG8_ABASE(nxt) : cA; const char* nB = has_next ? (const char*)Bt + (size_t)nxt.pn * tstepB : cB;
;         for (int t = 0; t < nt; t += 2) {
;             const bool last = (t == nt - 2);
;             const char* a1 = cA + (size_t)(t + 1) * kstep;
;             const char* a2 = last ? nA : cA + (size_t)(t + 2) * kstep; const char* b2 = last ? nB : cB + (size_t)(t + 2) * kstep;
;             const char* a3 = a2 + kstep; const char* b3 = b2 + kstep;
;             PG8_LDB(B0, 0, 0); PG8_SCHED; PG8_LDA(At, 0, 0); PG8_STAGE(PG8_SA(1, 1), a1 + hstepA, voffA);
;             PG8_WAIT_L(8); PG8_BAR; PG8_WAIT_L(0); PG8_MMA(0, 0, At, B0); PG8_BAR; PG8_SCHED;
;             PG8_LDB(B1, 0, 1); PG8_STAGE(PG8_SB(0, 0), b2, voffB);
;             PG8_BAR; PG8_WAIT_L(0); PG8_MMA(0, 1, At, B1); PG8_BAR;
;             PG8_LDA(At, 0, 1); PG8_STAGE(PG8_SA(0, 0), a2, voffA);
;             PG8_BAR; PG8_WAIT_L(0); PG8_MMA(1, 0, At, B0); PG8_BAR; PG8_SCHED;
;             PG8_STAGE(PG8_SB(0, 1), b2 + hstepB, voffB);
;             PG8_WAIT_V(6); PG8_BAR; PG8_MMA(1, 1, At, B1); PG8_BAR;
.LBB0_1081:
	ds_read_b128 v[146:149], v140
	ds_read_b128 v[150:153], v140 offset:1024
	ds_read_b128 v[160:163], v140 offset:2048
	ds_read_b128 v[166:169], v140 offset:3072
	s_mov_b32 m0, s57
	v_lshl_add_u64 v[156:157], v[136:137], 0, s[22:23]
	ds_read_b128 v[170:173], v141
	ds_read_b128 v[174:177], v141 offset:1024
	ds_read_b128 v[178:181], v141 offset:2048
	ds_read_b128 v[182:185], v141 offset:3072
	ds_read_b128 v[186:189], v141 offset:4096
	ds_read_b128 v[190:193], v141 offset:5120
	ds_read_b128 v[194:197], v141 offset:6144
	ds_read_b128 v[202:205], v141 offset:7168
	global_load_lds_dwordx4 v[156:157], off
	v_lshl_add_u64 v[156:157], v[138:139], 0, s[22:23]
	s_mov_b32 m0, s58
	s_nop 0
	global_load_lds_dwordx4 v[156:157], off
	s_waitcnt lgkmcnt(8)
	s_barrier
	s_waitcnt lgkmcnt(0)
	s_setprio 1
	s_waitcnt lgkmcnt(0)
	v_mfma_f32_16x16x32_bf16 v[124:127], v[146:149], v[170:173], v[124:127]
	v_mfma_f32_16x16x32_bf16 v[120:123], v[160:163], v[170:173], v[120:123]
	v_mfma_f32_16x16x32_bf16 v[112:115], v[146:149], v[178:181], v[112:115]
	v_mfma_f32_16x16x32_bf16 v[104:107], v[160:163], v[178:181], v[104:107]
	v_mfma_f32_16x16x32_bf16 v[96:99], v[146:149], v[186:189], v[96:99]
	v_mfma_f32_16x16x32_bf16 v[88:91], v[160:163], v[186:189], v[88:91]
	v_mfma_f32_16x16x32_bf16 v[80:83], v[146:149], v[194:197], v[80:83]
	v_mfma_f32_16x16x32_bf16 v[72:75], v[160:163], v[194:197], v[72:75]
	v_mfma_f32_16x16x32_bf16 v[124:127], v[150:153], v[174:177], v[124:127]
	v_mfma_f32_16x16x32_bf16 v[120:123], v[166:169], v[174:177], v[120:123]
	v_mfma_f32_16x16x32_bf16 v[112:115], v[150:153], v[182:185], v[112:115]
	v_mfma_f32_16x16x32_bf16 v[104:107], v[166:169], v[182:185], v[104:107]
	v_mfma_f32_16x16x32_bf16 v[96:99], v[150:153], v[190:193], v[96:99]
	v_mfma_f32_16x16x32_bf16 v[88:91], v[166:169], v[190:193], v[88:91]
	v_mfma_f32_16x16x32_bf16 v[80:83], v[150:153], v[202:205], v[80:83]
	v_mfma_f32_16x16x32_bf16 v[72:75], v[166:169], v[202:205], v[72:75]
	s_setprio 0
	s_barrier
	s_add_u32 s28, s22, 0xdfa80080
	s_addc_u32 s29, s23, -1
	s_cmp_lg_u32 s56, 28
	s_cselect_b32 s28, s28, 0
	s_cselect_b32 s29, s29, 0
	s_add_u32 s46, s0, s28
	s_addc_u32 s47, s1, s29
	s_add_u32 s44, s2, s28
	s_addc_u32 s45, s3, s29
	s_mov_b32 m0, s59
	s_add_u32 s98, s44, s42
	s_addc_u32 s99, s45, s43
	ds_read_b128 v[206:209], v142
	ds_read_b128 v[210:213], v142 offset:1024
	ds_read_b128 v[214:217], v142 offset:2048
	ds_read_b128 v[218:221], v142 offset:3072
	global_load_lds_dwordx4 v130, s[44:45]
	s_mov_b32 m0, s60
	s_nop 0
	global_load_lds_dwordx4 v134, s[44:45]
	s_barrier
	s_waitcnt lgkmcnt(0)
	s_setprio 1
	s_waitcnt lgkmcnt(0)
	v_mfma_f32_16x16x32_bf16 v[116:119], v[206:209], v[170:173], v[116:119]
	v_mfma_f32_16x16x32_bf16 v[108:111], v[214:217], v[170:173], v[108:111]
	v_mfma_f32_16x16x32_bf16 v[100:103], v[206:209], v[178:181], v[100:103]
	v_mfma_f32_16x16x32_bf16 v[92:95], v[214:217], v[178:181], v[92:95]
	v_mfma_f32_16x16x32_bf16 v[84:87], v[206:209], v[186:189], v[84:87]
	v_mfma_f32_16x16x32_bf16 v[76:79], v[214:217], v[186:189], v[76:79]
	v_mfma_f32_16x16x32_bf16 v[68:71], v[206:209], v[194:197], v[68:71]
	v_mfma_f32_16x16x32_bf16 v[64:67], v[214:217], v[194:197], v[64:67]
	v_mfma_f32_16x16x32_bf16 v[116:119], v[210:213], v[174:177], v[116:119]
	v_mfma_f32_16x16x32_bf16 v[108:111], v[218:221], v[174:177], v[108:111]
	v_mfma_f32_16x16x32_bf16 v[100:103], v[210:213], v[182:185], v[100:103]
	v_mfma_f32_16x16x32_bf16 v[92:95], v[218:221], v[182:185], v[92:95]
	v_mfma_f32_16x16x32_bf16 v[84:87], v[210:213], v[190:193], v[84:87]
	v_mfma_f32_16x16x32_bf16 v[76:79], v[218:221], v[190:193], v[76:79]
	v_mfma_f32_16x16x32_bf16 v[68:71], v[210:213], v[202:205], v[68:71]
	v_mfma_f32_16x16x32_bf16 v[64:67], v[218:221], v[202:205], v[64:67]
	s_setprio 0
	s_mov_b32 m0, s49
	s_add_u32 s100, s46, s42
	s_addc_u32 s101, s47, s43
	s_barrier
	ds_read_b128 v[170:173], v141 offset:16384
	ds_read_b128 v[174:177], v141 offset:17408
	ds_read_b128 v[178:181], v141 offset:18432
	ds_read_b128 v[182:185], v141 offset:19456
	ds_read_b128 v[186:189], v141 offset:20480
	ds_read_b128 v[190:193], v141 offset:21504
	ds_read_b128 v[194:197], v141 offset:22528
	ds_read_b128 v[202:205], v141 offset:23552
	global_load_lds_dwordx4 v128, s[46:47]
	s_mov_b32 m0, s50
	s_nop 0
	global_load_lds_dwordx4 v132, s[46:47]
	s_barrier
	s_waitcnt lgkmcnt(0)
	s_setprio 1
	s_waitcnt lgkmcnt(0)
	v_mfma_f32_16x16x32_bf16 v[60:63], v[146:149], v[170:173], v[60:63]
	v_mfma_f32_16x16x32_bf16 v[56:59], v[160:163], v[170:173], v[56:59]
	v_mfma_f32_16x16x32_bf16 v[48:51], v[146:149], v[178:181], v[48:51]
	v_mfma_f32_16x16x32_bf16 v[40:43], v[160:163], v[178:181], v[40:43]
	v_mfma_f32_16x16x32_bf16 v[32:35], v[146:149], v[186:189], v[32:35]
	v_mfma_f32_16x16x32_bf16 v[24:27], v[160:163], v[186:189], v[24:27]
	v_mfma_f32_16x16x32_bf16 v[16:19], v[146:149], v[194:197], v[16:19]
	v_mfma_f32_16x16x32_bf16 v[8:11], v[160:163], v[194:197], v[8:11]
	v_mfma_f32_16x16x32_bf16 v[60:63], v[150:153], v[174:177], v[60:63]
	v_mfma_f32_16x16x32_bf16 v[56:59], v[166:169], v[174:177], v[56:59]
	v_mfma_f32_16x16x32_bf16 v[48:51], v[150:153], v[182:185], v[48:51]
	v_mfma_f32_16x16x32_bf16 v[40:43], v[166:169], v[182:185], v[40:43]
	v_mfma_f32_16x16x32_bf16 v[32:35], v[150:153], v[190:193], v[32:35]
	v_mfma_f32_16x16x32_bf16 v[24:27], v[166:169], v[190:193], v[24:27]
	v_mfma_f32_16x16x32_bf16 v[16:19], v[150:153], v[202:205], v[16:19]
	v_mfma_f32_16x16x32_bf16 v[8:11], v[166:169], v[202:205], v[8:11]
	s_setprio 0
	s_barrier
	s_add_u32 s28, s44, 0x80000
	s_addc_u32 s29, s45, 0
	s_mov_b32 m0, s61
	s_nop 0
	global_load_lds_dwordx4 v130, s[28:29]
	s_mov_b32 m0, s62
	s_nop 0
	global_load_lds_dwordx4 v134, s[28:29]
	s_waitcnt vmcnt(6)
	s_barrier
; #define PG8_STAGE(bufoff, gbase, voff) do { _Pragma("unroll") for (int _i = 0; _i < 2; ++_i) \
;         __builtin_amdgcn_global_load_lds((const unsigned*)((const char*)(gbase) + (voff)[_i]), (LAS unsigned*)(lds + (bufoff) + ldsw + _i * 8192), 16, 0, 0); } while (0)
; #define PG8_LDA(dst, b, h) do { _Pragma("unroll") for (int m = 0; m < 4; ++m) _Pragma("unroll") for (int k = 0; k < 2; ++k) dst[m][k] = *(const LAS bf16x8*)(lds + PG8_SA(b, h) + aoff + m * 2048 + k * 1024); } while (0)
; #define PG8_LDB(dst, b, h) do { _Pragma("unroll") for (int n = 0; n < 2; ++n) _Pragma("unroll") for (int k = 0; k < 2; ++k) dst[n][k] = *(const LAS bf16x8*)(lds + PG8_SB(b, h) + boff + n * 2048 + k * 1024); } while (0)
; #define PG8_WAIT_V(n) asm volatile("s_waitcnt vmcnt(" #n ")" ::: "memory")
; #define PG8_WAIT_L(n) asm volatile("s_waitcnt lgkmcnt(" #n ")" ::: "memory")
; #define PG8_BAR __builtin_amdgcn_s_barrier()
; #define PG8_SCHED __builtin_amdgcn_sched_barrier(0)
; template <class Epi>
; __device__ __forceinline__ void gemm_phase(LAS unsigned char* lds, const bf16_t* A, int lda, const bf16_t* Bt, int ldb, int M, int N, int K, int asel, const Epi& E, const int fixed_round = -1) {
;     ...
;             PG8_WAIT_V(6); PG8_BAR; PG8_MMA(1, 1, At, B1); PG8_BAR;
;             PG8_LDB(B0, 1, 0); PG8_SCHED; PG8_LDA(At, 1, 0); PG8_STAGE(PG8_SA(0, 1), a2 + hstepA, voffA);
;             PG8_WAIT_L(8); PG8_BAR; PG8_WAIT_L(0); PG8_MMA(0, 0, At, B0); PG8_BAR; PG8_SCHED;
;             PG8_LDB(B1, 1, 1); PG8_STAGE(PG8_SB(1, 0), b3, voffB);
;             PG8_BAR; PG8_WAIT_L(0); PG8_MMA(0, 1, At, B1); PG8_BAR;
	s_setprio 1
	v_mfma_f32_16x16x32_bf16 v[52:55], v[206:209], v[170:173], v[52:55]
	v_mfma_f32_16x16x32_bf16 v[44:47], v[214:217], v[170:173], v[44:47]
	v_mfma_f32_16x16x32_bf16 v[36:39], v[206:209], v[178:181], v[36:39]
	v_mfma_f32_16x16x32_bf16 v[28:31], v[214:217], v[178:181], v[28:31]
	v_mfma_f32_16x16x32_bf16 v[20:23], v[206:209], v[186:189], v[20:23]
	v_mfma_f32_16x16x32_bf16 v[12:15], v[214:217], v[186:189], v[12:15]
	v_mfma_f32_16x16x32_bf16 v[4:7], v[206:209], v[194:197], v[4:7]
	v_mfma_f32_16x16x32_bf16 v[0:3], v[214:217], v[194:197], v[0:3]
	v_mfma_f32_16x16x32_bf16 v[52:55], v[210:213], v[174:177], v[52:55]
	v_mfma_f32_16x16x32_bf16 v[44:47], v[218:221], v[174:177], v[44:47]
	v_mfma_f32_16x16x32_bf16 v[36:39], v[210:213], v[182:185], v[36:39]
	v_mfma_f32_16x16x32_bf16 v[28:31], v[218:221], v[182:185], v[28:31]
	v_mfma_f32_16x16x32_bf16 v[20:23], v[210:213], v[190:193], v[20:23]
	v_mfma_f32_16x16x32_bf16 v[12:15], v[218:221], v[190:193], v[12:15]
	v_mfma_f32_16x16x32_bf16 v[4:7], v[210:213], v[202:205], v[4:7]
	v_mfma_f32_16x16x32_bf16 v[0:3], v[218:221], v[202:205], v[0:3]
	s_setprio 0
	s_barrier
	ds_read_b128 v[146:149], v143
	ds_read_b128 v[150:153], v143 offset:1024
	ds_read_b128 v[160:163], v143 offset:2048
	ds_read_b128 v[166:169], v143 offset:3072
	s_add_u32 s28, s46, 0x80000
	s_addc_u32 s29, s47, 0
	s_mov_b32 m0, s52
	ds_read_b128 v[170:173], v141 offset:32768
	ds_read_b128 v[174:177], v141 offset:33792
	ds_read_b128 v[178:181], v141 offset:34816
	ds_read_b128 v[182:185], v141 offset:35840
	ds_read_b128 v[186:189], v141 offset:36864
	ds_read_b128 v[190:193], v141 offset:37888
	ds_read_b128 v[194:197], v141 offset:38912
	ds_read_b128 v[202:205], v141 offset:39936
	global_load_lds_dwordx4 v128, s[28:29]
	s_mov_b32 m0, s53
	s_nop 0
	global_load_lds_dwordx4 v132, s[28:29]
	s_waitcnt lgkmcnt(8)
	s_barrier
	s_waitcnt lgkmcnt(0)
	s_setprio 1
	s_waitcnt lgkmcnt(0)
	v_mfma_f32_16x16x32_bf16 v[124:127], v[146:149], v[170:173], v[124:127]
	v_mfma_f32_16x16x32_bf16 v[120:123], v[160:163], v[170:173], v[120:123]
	v_mfma_f32_16x16x32_bf16 v[112:115], v[146:149], v[178:181], v[112:115]
	v_mfma_f32_16x16x32_bf16 v[104:107], v[160:163], v[178:181], v[104:107]
	v_mfma_f32_16x16x32_bf16 v[96:99], v[146:149], v[186:189], v[96:99]
	v_mfma_f32_16x16x32_bf16 v[88:91], v[160:163], v[186:189], v[88:91]
	v_mfma_f32_16x16x32_bf16 v[80:83], v[146:149], v[194:197], v[80:83]
	v_mfma_f32_16x16x32_bf16 v[72:75], v[160:163], v[194:197], v[72:75]
	v_mfma_f32_16x16x32_bf16 v[124:127], v[150:153], v[174:177], v[124:127]
	v_mfma_f32_16x16x32_bf16 v[120:123], v[166:169], v[174:177], v[120:123]
	v_mfma_f32_16x16x32_bf16 v[112:115], v[150:153], v[182:185], v[112:115]
	v_mfma_f32_16x16x32_bf16 v[104:107], v[166:169], v[182:185], v[104:107]
	v_mfma_f32_16x16x32_bf16 v[96:99], v[150:153], v[190:193], v[96:99]
	v_mfma_f32_16x16x32_bf16 v[88:91], v[166:169], v[190:193], v[88:91]
	v_mfma_f32_16x16x32_bf16 v[80:83], v[150:153], v[202:205], v[80:83]
	v_mfma_f32_16x16x32_bf16 v[72:75], v[166:169], v[202:205], v[72:75]
	s_setprio 0
	s_barrier
	s_mov_b32 m0, s63
	ds_read_b128 v[206:209], v144
	ds_read_b128 v[210:213], v144 offset:1024
	ds_read_b128 v[214:217], v144 offset:2048
	ds_read_b128 v[218:221], v144 offset:3072
	global_load_lds_dwordx4 v130, s[98:99]
	s_mov_b32 m0, s64
	s_nop 0
	global_load_lds_dwordx4 v134, s[98:99]
	s_barrier
; #define PG8_STAGE(bufoff, gbase, voff) do { _Pragma("unroll") for (int _i = 0; _i < 2; ++_i) \
;         __builtin_amdgcn_global_load_lds((const unsigned*)((const char*)(gbase) + (voff)[_i]), (LAS unsigned*)(lds + (bufoff) + ldsw + _i * 8192), 16, 0, 0); } while (0)
; #define PG8_LDA(dst, b, h) do { _Pragma("unroll") for (int m = 0; m < 4; ++m) _Pragma("unroll") for (int k = 0; k < 2; ++k) dst[m][k] = *(const LAS bf16x8*)(lds + PG8_SA(b, h) + aoff + m * 2048 + k * 1024); } while (0)
; #define PG8_WAIT_V(n) asm volatile("s_waitcnt vmcnt(" #n ")" ::: "memory")
; #define PG8_WAIT_L(n) asm volatile("s_waitcnt lgkmcnt(" #n ")" ::: "memory")
; #define PG8_BAR __builtin_amdgcn_s_barrier()
; #define PG8_SCHED __builtin_amdgcn_sched_barrier(0)
; template <class Epi>
; __device__ __forceinline__ void gemm_phase(LAS unsigned char* lds, const bf16_t* A, int lda, const bf16_t* Bt, int ldb, int M, int N, int K, int asel, const Epi& E, const int fixed_round = -1) {
;     ...
;             PG8_BAR; PG8_WAIT_L(0); PG8_MMA(0, 1, At, B1); PG8_BAR;
;             PG8_LDA(At, 1, 1); PG8_STAGE(PG8_SA(1, 0), a3, voffA);
;             PG8_BAR; PG8_WAIT_L(0); PG8_MMA(1, 0, At, B0); PG8_BAR; PG8_SCHED;
;             PG8_STAGE(PG8_SB(1, 1), b3 + hstepB, voffB);
;             PG8_WAIT_V(6); PG8_BAR; PG8_MMA(1, 1, At, B1); PG8_BAR;
;     ...
;     PG8_WAIT_V(0);
;     if (wr == 0) PG8_BAR;
;     PG8_BAR;
	s_waitcnt lgkmcnt(0)
	s_setprio 1
	s_waitcnt lgkmcnt(0)
	v_mfma_f32_16x16x32_bf16 v[116:119], v[206:209], v[170:173], v[116:119]
	v_mfma_f32_16x16x32_bf16 v[108:111], v[214:217], v[170:173], v[108:111]
	v_mfma_f32_16x16x32_bf16 v[100:103], v[206:209], v[178:181], v[100:103]
	v_mfma_f32_16x16x32_bf16 v[92:95], v[214:217], v[178:181], v[92:95]
	v_mfma_f32_16x16x32_bf16 v[84:87], v[206:209], v[186:189], v[84:87]
	v_mfma_f32_16x16x32_bf16 v[76:79], v[214:217], v[186:189], v[76:79]
	v_mfma_f32_16x16x32_bf16 v[68:71], v[206:209], v[194:197], v[68:71]
	v_mfma_f32_16x16x32_bf16 v[64:67], v[214:217], v[194:197], v[64:67]
	v_mfma_f32_16x16x32_bf16 v[116:119], v[210:213], v[174:177], v[116:119]
	v_mfma_f32_16x16x32_bf16 v[108:111], v[218:221], v[174:177], v[108:111]
	v_mfma_f32_16x16x32_bf16 v[100:103], v[210:213], v[182:185], v[100:103]
	v_mfma_f32_16x16x32_bf16 v[92:95], v[218:221], v[182:185], v[92:95]
	v_mfma_f32_16x16x32_bf16 v[84:87], v[210:213], v[190:193], v[84:87]
	v_mfma_f32_16x16x32_bf16 v[76:79], v[218:221], v[190:193], v[76:79]
	v_mfma_f32_16x16x32_bf16 v[68:71], v[210:213], v[202:205], v[68:71]
	v_mfma_f32_16x16x32_bf16 v[64:67], v[218:221], v[202:205], v[64:67]
	s_setprio 0
	s_mov_b32 m0, s54
	s_barrier
	ds_read_b128 v[170:173], v141 offset:49152
	ds_read_b128 v[174:177], v141 offset:50176
	ds_read_b128 v[178:181], v141 offset:51200
	ds_read_b128 v[182:185], v141 offset:52224
	ds_read_b128 v[186:189], v141 offset:53248
	ds_read_b128 v[190:193], v141 offset:54272
	ds_read_b128 v[194:197], v141 offset:55296
	ds_read_b128 v[202:205], v141 offset:56320
	global_load_lds_dwordx4 v128, s[100:101]
	s_mov_b32 m0, s55
	s_nop 0
	global_load_lds_dwordx4 v132, s[100:101]
	s_barrier
	s_waitcnt lgkmcnt(0)
	s_setprio 1
	s_waitcnt lgkmcnt(0)
	v_mfma_f32_16x16x32_bf16 v[60:63], v[146:149], v[170:173], v[60:63]
	v_mfma_f32_16x16x32_bf16 v[56:59], v[160:163], v[170:173], v[56:59]
	v_mfma_f32_16x16x32_bf16 v[48:51], v[146:149], v[178:181], v[48:51]
	v_mfma_f32_16x16x32_bf16 v[40:43], v[160:163], v[178:181], v[40:43]
	v_mfma_f32_16x16x32_bf16 v[32:35], v[146:149], v[186:189], v[32:35]
	v_mfma_f32_16x16x32_bf16 v[24:27], v[160:163], v[186:189], v[24:27]
	v_mfma_f32_16x16x32_bf16 v[16:19], v[146:149], v[194:197], v[16:19]
	v_mfma_f32_16x16x32_bf16 v[8:11], v[160:163], v[194:197], v[8:11]
	v_mfma_f32_16x16x32_bf16 v[60:63], v[150:153], v[174:177], v[60:63]
	v_mfma_f32_16x16x32_bf16 v[56:59], v[166:169], v[174:177], v[56:59]
	v_mfma_f32_16x16x32_bf16 v[48:51], v[150:153], v[182:185], v[48:51]
	v_mfma_f32_16x16x32_bf16 v[40:43], v[166:169], v[182:185], v[40:43]
	v_mfma_f32_16x16x32_bf16 v[32:35], v[150:153], v[190:193], v[32:35]
	v_mfma_f32_16x16x32_bf16 v[24:27], v[166:169], v[190:193], v[24:27]
	v_mfma_f32_16x16x32_bf16 v[16:19], v[150:153], v[202:205], v[16:19]
	v_mfma_f32_16x16x32_bf16 v[8:11], v[166:169], v[202:205], v[8:11]
	s_setprio 0
	s_barrier
	s_add_u32 s28, s44, 0x80080
	s_addc_u32 s29, s45, 0
	s_mov_b32 m0, s65
	s_nop 0
	global_load_lds_dwordx4 v130, s[28:29]
	s_mov_b32 m0, s66
	s_nop 0
	global_load_lds_dwordx4 v134, s[28:29]
	s_waitcnt vmcnt(6)
	s_barrier
	s_setprio 1
	v_mfma_f32_16x16x32_bf16 v[52:55], v[206:209], v[170:173], v[52:55]
	v_mfma_f32_16x16x32_bf16 v[44:47], v[214:217], v[170:173], v[44:47]
	v_mfma_f32_16x16x32_bf16 v[36:39], v[206:209], v[178:181], v[36:39]
	v_mfma_f32_16x16x32_bf16 v[28:31], v[214:217], v[178:181], v[28:31]
	v_mfma_f32_16x16x32_bf16 v[20:23], v[206:209], v[186:189], v[20:23]
	v_mfma_f32_16x16x32_bf16 v[12:15], v[214:217], v[186:189], v[12:15]
	v_mfma_f32_16x16x32_bf16 v[4:7], v[206:209], v[194:197], v[4:7]
	v_mfma_f32_16x16x32_bf16 v[0:3], v[214:217], v[194:197], v[0:3]
	v_mfma_f32_16x16x32_bf16 v[52:55], v[210:213], v[174:177], v[52:55]
	v_mfma_f32_16x16x32_bf16 v[44:47], v[218:221], v[174:177], v[44:47]
	v_mfma_f32_16x16x32_bf16 v[36:39], v[210:213], v[182:185], v[36:39]
	v_mfma_f32_16x16x32_bf16 v[28:31], v[218:221], v[182:185], v[28:31]
	v_mfma_f32_16x16x32_bf16 v[20:23], v[210:213], v[190:193], v[20:23]
	v_mfma_f32_16x16x32_bf16 v[12:15], v[218:221], v[190:193], v[12:15]
	v_mfma_f32_16x16x32_bf16 v[4:7], v[210:213], v[202:205], v[4:7]
	v_mfma_f32_16x16x32_bf16 v[0:3], v[218:221], v[202:205], v[0:3]
	s_setprio 0
	s_add_i32 s56, s56, 2
	s_add_u32 s22, s22, 0x100
	s_addc_u32 s23, s23, 0
	s_cmp_lt_u32 s56, 30
	s_cbranch_scc1 .Lrot_8
	s_barrier
	s_waitcnt vmcnt(0)
	s_cmpk_gt_u32 s48, 0xff
	s_cbranch_scc1 .LBB0_1084
	s_barrier

; #define PG8_STAGE(bufoff, gbase, voff) do { _Pragma("unroll") for (int _i = 0; _i < 2; ++_i) \
;         __builtin_amdgcn_global_load_lds((const unsigned*)((const char*)(gbase) + (voff)[_i]), (LAS unsigned*)(lds + (bufoff) + ldsw + _i * 8192), 16, 0, 0); } while (0)
; #define PG8_LDA(dst, b, h) do { _Pragma("unroll") for (int m = 0; m < 4; ++m) _Pragma("unroll") for (int k = 0; k < 2; ++k) dst[m][k] = *(const LAS bf16x8*)(lds + PG8_SA(b, h) + aoff + m * 2048 + k * 1024); } while (0)
; #define PG8_LDB(dst, b, h) do { _Pragma("unroll") for (int n = 0; n < 2; ++n) _Pragma("unroll") for (int k = 0; k < 2; ++k) dst[n][k] = *(const LAS bf16x8*)(lds + PG8_SB(b, h) + boff + n * 2048 + k * 1024); } while (0)
; #define PG8_WAIT_V(n) asm volatile("s_waitcnt vmcnt(" #n ")" ::: "memory")
; #define PG8_WAIT_L(n) asm volatile("s_waitcnt lgkmcnt(" #n ")" ::: "memory")
; #define PG8_BAR __builtin_amdgcn_s_barrier()
; #define PG8_SCHED __builtin_amdgcn_sched_barrier(0)
; template <class Epi>
; __device__ __forceinline__ void gemm_phase(LAS unsigned char* lds, const bf16_t* A, int lda, const bf16_t* Bt, int ldb, int M, int N, int K, int asel, const Epi& E, const int fixed_round = -1) {
;     ...
;         const char* nA = has_next ? PG8_ABASE(nxt) : cA; const char* nB = has_next ? (const char*)Bt + (size_t)nxt.pn * tstepB : cB;
;         for (int t = 0; t < nt; t += 2) {
;             const bool last = (t == nt - 2);
;             const char* a1 = cA + (size_t)(t + 1) * kstep;
;             const char* a2 = last ? nA : cA + (size_t)(t + 2) * kstep; const char* b2 = last ? nB : cB + (size_t)(t + 2) * kstep;
;             const char* a3 = a2 + kstep; const char* b3 = b2 + kstep;
;             PG8_LDB(B0, 0, 0); PG8_SCHED; PG8_LDA(At, 0, 0); PG8_STAGE(PG8_SA(1, 1), a1 + hstepA, voffA);
;             PG8_WAIT_L(8); PG8_BAR; PG8_WAIT_L(0); PG8_MMA(0, 0, At, B0); PG8_BAR; PG8_SCHED;
;             PG8_LDB(B1, 0, 1); PG8_STAGE(PG8_SB(0, 0), b2, voffB);
;             PG8_BAR; PG8_WAIT_L(0); PG8_MMA(0, 1, At, B1); PG8_BAR;
;             PG8_LDA(At, 0, 1); PG8_STAGE(PG8_SA(0, 0), a2, voffA);
;             PG8_BAR; PG8_WAIT_L(0); PG8_MMA(1, 0, At, B0); PG8_BAR; PG8_SCHED;
;             PG8_STAGE(PG8_SB(0, 1), b2 + hstepB, voffB);
;             PG8_WAIT_V(6); PG8_BAR; PG8_MMA(1, 1, At, B1); PG8_BAR;
.LBB0_1120:
	ds_read_b128 v[146:149], v138
	ds_read_b128 v[150:153], v138 offset:1024
	ds_read_b128 v[160:163], v138 offset:2048
	ds_read_b128 v[166:169], v138 offset:3072
	s_mov_b32 m0, s41
	v_lshl_add_u64 v[156:157], v[134:135], 0, s[6:7]
	ds_read_b128 v[170:173], v139
	ds_read_b128 v[174:177], v139 offset:1024
	ds_read_b128 v[178:181], v139 offset:2048
	ds_read_b128 v[182:185], v139 offset:3072
	ds_read_b128 v[186:189], v139 offset:4096
	ds_read_b128 v[190:193], v139 offset:5120
	ds_read_b128 v[194:197], v139 offset:6144
	ds_read_b128 v[202:205], v139 offset:7168
	global_load_lds_dwordx4 v[156:157], off
	v_lshl_add_u64 v[156:157], v[136:137], 0, s[6:7]
	s_mov_b32 m0, s58
	s_nop 0
	global_load_lds_dwordx4 v[156:157], off
	s_waitcnt lgkmcnt(8)
	s_barrier
	s_waitcnt lgkmcnt(0)
	s_setprio 1
	s_waitcnt lgkmcnt(0)
	v_mfma_f32_16x16x32_bf16 v[124:127], v[146:149], v[170:173], v[124:127]
	v_mfma_f32_16x16x32_bf16 v[120:123], v[160:163], v[170:173], v[120:123]
	v_mfma_f32_16x16x32_bf16 v[112:115], v[146:149], v[178:181], v[112:115]
	v_mfma_f32_16x16x32_bf16 v[104:107], v[160:163], v[178:181], v[104:107]
	v_mfma_f32_16x16x32_bf16 v[96:99], v[146:149], v[186:189], v[96:99]
	v_mfma_f32_16x16x32_bf16 v[88:91], v[160:163], v[186:189], v[88:91]
	v_mfma_f32_16x16x32_bf16 v[80:83], v[146:149], v[194:197], v[80:83]
	v_mfma_f32_16x16x32_bf16 v[72:75], v[160:163], v[194:197], v[72:75]
	v_mfma_f32_16x16x32_bf16 v[124:127], v[150:153], v[174:177], v[124:127]
	v_mfma_f32_16x16x32_bf16 v[120:123], v[166:169], v[174:177], v[120:123]
	v_mfma_f32_16x16x32_bf16 v[112:115], v[150:153], v[182:185], v[112:115]
	v_mfma_f32_16x16x32_bf16 v[104:107], v[166:169], v[182:185], v[104:107]
	v_mfma_f32_16x16x32_bf16 v[96:99], v[150:153], v[190:193], v[96:99]
	v_mfma_f32_16x16x32_bf16 v[88:91], v[166:169], v[190:193], v[88:91]
	v_mfma_f32_16x16x32_bf16 v[80:83], v[150:153], v[202:205], v[80:83]
	v_mfma_f32_16x16x32_bf16 v[72:75], v[166:169], v[202:205], v[72:75]
	s_setprio 0
	s_barrier
	s_add_u32 s22, s6, 0xdfa80080
	s_addc_u32 s23, s7, -1
	s_cmp_lg_u32 s40, 28
	s_cselect_b32 s22, s22, 0
	s_cselect_b32 s23, s23, 0
	s_add_u32 s24, s0, s22
	s_addc_u32 s25, s1, s23
	s_add_u32 s22, s2, s22
	s_addc_u32 s23, s3, s23
	s_mov_b32 m0, s59
	s_add_u32 s98, s22, s4
	s_addc_u32 s99, s23, s5
	ds_read_b128 v[206:209], v140
	ds_read_b128 v[210:213], v140 offset:1024
	ds_read_b128 v[214:217], v140 offset:2048
	ds_read_b128 v[218:221], v140 offset:3072
	global_load_lds_dwordx4 v144, s[22:23]
	s_mov_b32 m0, s60
	s_nop 0
	global_load_lds_dwordx4 v132, s[22:23]
	s_barrier
	s_waitcnt lgkmcnt(0)
	s_setprio 1
	s_waitcnt lgkmcnt(0)
	v_mfma_f32_16x16x32_bf16 v[116:119], v[206:209], v[170:173], v[116:119]
	v_mfma_f32_16x16x32_bf16 v[108:111], v[214:217], v[170:173], v[108:111]
	v_mfma_f32_16x16x32_bf16 v[100:103], v[206:209], v[178:181], v[100:103]
	v_mfma_f32_16x16x32_bf16 v[92:95], v[214:217], v[178:181], v[92:95]
	v_mfma_f32_16x16x32_bf16 v[84:87], v[206:209], v[186:189], v[84:87]
	v_mfma_f32_16x16x32_bf16 v[76:79], v[214:217], v[186:189], v[76:79]
	v_mfma_f32_16x16x32_bf16 v[68:71], v[206:209], v[194:197], v[68:71]
	v_mfma_f32_16x16x32_bf16 v[64:67], v[214:217], v[194:197], v[64:67]
	v_mfma_f32_16x16x32_bf16 v[116:119], v[210:213], v[174:177], v[116:119]
	v_mfma_f32_16x16x32_bf16 v[108:111], v[218:221], v[174:177], v[108:111]
	v_mfma_f32_16x16x32_bf16 v[100:103], v[210:213], v[182:185], v[100:103]
	v_mfma_f32_16x16x32_bf16 v[92:95], v[218:221], v[182:185], v[92:95]
	v_mfma_f32_16x16x32_bf16 v[84:87], v[210:213], v[190:193], v[84:87]
	v_mfma_f32_16x16x32_bf16 v[76:79], v[218:221], v[190:193], v[76:79]
	v_mfma_f32_16x16x32_bf16 v[68:71], v[210:213], v[202:205], v[68:71]
	v_mfma_f32_16x16x32_bf16 v[64:67], v[218:221], v[202:205], v[64:67]
	s_setprio 0
	s_mov_b32 m0, s52
	s_add_u32 s100, s24, s4
	s_addc_u32 s101, s25, s5
	s_barrier
	ds_read_b128 v[170:173], v139 offset:16384
	ds_read_b128 v[174:177], v139 offset:17408
	ds_read_b128 v[178:181], v139 offset:18432
	ds_read_b128 v[182:185], v139 offset:19456
	ds_read_b128 v[186:189], v139 offset:20480
	ds_read_b128 v[190:193], v139 offset:21504
	ds_read_b128 v[194:197], v139 offset:22528
	ds_read_b128 v[202:205], v139 offset:23552
	global_load_lds_dwordx4 v128, s[24:25]
	s_mov_b32 m0, s53
	s_nop 0
	global_load_lds_dwordx4 v130, s[24:25]
	s_barrier
	s_waitcnt lgkmcnt(0)
	s_setprio 1
	s_waitcnt lgkmcnt(0)
	v_mfma_f32_16x16x32_bf16 v[60:63], v[146:149], v[170:173], v[60:63]
	v_mfma_f32_16x16x32_bf16 v[56:59], v[160:163], v[170:173], v[56:59]
	v_mfma_f32_16x16x32_bf16 v[48:51], v[146:149], v[178:181], v[48:51]
	v_mfma_f32_16x16x32_bf16 v[40:43], v[160:163], v[178:181], v[40:43]
	v_mfma_f32_16x16x32_bf16 v[32:35], v[146:149], v[186:189], v[32:35]
	v_mfma_f32_16x16x32_bf16 v[24:27], v[160:163], v[186:189], v[24:27]
	v_mfma_f32_16x16x32_bf16 v[16:19], v[146:149], v[194:197], v[16:19]
	v_mfma_f32_16x16x32_bf16 v[8:11], v[160:163], v[194:197], v[8:11]
	v_mfma_f32_16x16x32_bf16 v[60:63], v[150:153], v[174:177], v[60:63]
	v_mfma_f32_16x16x32_bf16 v[56:59], v[166:169], v[174:177], v[56:59]
	v_mfma_f32_16x16x32_bf16 v[48:51], v[150:153], v[182:185], v[48:51]
	v_mfma_f32_16x16x32_bf16 v[40:43], v[166:169], v[182:185], v[40:43]
	v_mfma_f32_16x16x32_bf16 v[32:35], v[150:153], v[190:193], v[32:35]
	v_mfma_f32_16x16x32_bf16 v[24:27], v[166:169], v[190:193], v[24:27]
	v_mfma_f32_16x16x32_bf16 v[16:19], v[150:153], v[202:205], v[16:19]
	v_mfma_f32_16x16x32_bf16 v[8:11], v[166:169], v[202:205], v[8:11]
	s_setprio 0
	s_barrier
	s_add_u32 s28, s22, 0x80000
	s_addc_u32 s29, s23, 0
	s_mov_b32 m0, s61
	s_nop 0
	global_load_lds_dwordx4 v144, s[28:29]
	s_mov_b32 m0, s62
	s_nop 0
	global_load_lds_dwordx4 v132, s[28:29]
	s_waitcnt vmcnt(6)
	s_barrier
; #define PG8_STAGE(bufoff, gbase, voff) do { _Pragma("unroll") for (int _i = 0; _i < 2; ++_i) \
;         __builtin_amdgcn_global_load_lds((const unsigned*)((const char*)(gbase) + (voff)[_i]), (LAS unsigned*)(lds + (bufoff) + ldsw + _i * 8192), 16, 0, 0); } while (0)
; #define PG8_LDA(dst, b, h) do { _Pragma("unroll") for (int m = 0; m < 4; ++m) _Pragma("unroll") for (int k = 0; k < 2; ++k) dst[m][k] = *(const LAS bf16x8*)(lds + PG8_SA(b, h) + aoff + m * 2048 + k * 1024); } while (0)
; #define PG8_LDB(dst, b, h) do { _Pragma("unroll") for (int n = 0; n < 2; ++n) _Pragma("unroll") for (int k = 0; k < 2; ++k) dst[n][k] = *(const LAS bf16x8*)(lds + PG8_SB(b, h) + boff + n * 2048 + k * 1024); } while (0)
; #define PG8_WAIT_V(n) asm volatile("s_waitcnt vmcnt(" #n ")" ::: "memory")
; #define PG8_WAIT_L(n) asm volatile("s_waitcnt lgkmcnt(" #n ")" ::: "memory")
; #define PG8_BAR __builtin_amdgcn_s_barrier()
; #define PG8_SCHED __builtin_amdgcn_sched_barrier(0)
; template <class Epi>
; __device__ __forceinline__ void gemm_phase(LAS unsigned char* lds, const bf16_t* A, int lda, const bf16_t* Bt, int ldb, int M, int N, int K, int asel, const Epi& E, const int fixed_round = -1) {
;     ...
;             PG8_WAIT_V(6); PG8_BAR; PG8_MMA(1, 1, At, B1); PG8_BAR;
;             PG8_LDB(B0, 1, 0); PG8_SCHED; PG8_LDA(At, 1, 0); PG8_STAGE(PG8_SA(0, 1), a2 + hstepA, voffA);
;             PG8_WAIT_L(8); PG8_BAR; PG8_WAIT_L(0); PG8_MMA(0, 0, At, B0); PG8_BAR; PG8_SCHED;
;             PG8_LDB(B1, 1, 1); PG8_STAGE(PG8_SB(1, 0), b3, voffB);
;             PG8_BAR; PG8_WAIT_L(0); PG8_MMA(0, 1, At, B1); PG8_BAR;
	s_setprio 1
	v_mfma_f32_16x16x32_bf16 v[52:55], v[206:209], v[170:173], v[52:55]
	v_mfma_f32_16x16x32_bf16 v[44:47], v[214:217], v[170:173], v[44:47]
	v_mfma_f32_16x16x32_bf16 v[36:39], v[206:209], v[178:181], v[36:39]
	v_mfma_f32_16x16x32_bf16 v[28:31], v[214:217], v[178:181], v[28:31]
	v_mfma_f32_16x16x32_bf16 v[20:23], v[206:209], v[186:189], v[20:23]
	v_mfma_f32_16x16x32_bf16 v[12:15], v[214:217], v[186:189], v[12:15]
	v_mfma_f32_16x16x32_bf16 v[4:7], v[206:209], v[194:197], v[4:7]
	v_mfma_f32_16x16x32_bf16 v[0:3], v[214:217], v[194:197], v[0:3]
	v_mfma_f32_16x16x32_bf16 v[52:55], v[210:213], v[174:177], v[52:55]
	v_mfma_f32_16x16x32_bf16 v[44:47], v[218:221], v[174:177], v[44:47]
	v_mfma_f32_16x16x32_bf16 v[36:39], v[210:213], v[182:185], v[36:39]
	v_mfma_f32_16x16x32_bf16 v[28:31], v[218:221], v[182:185], v[28:31]
	v_mfma_f32_16x16x32_bf16 v[20:23], v[210:213], v[190:193], v[20:23]
	v_mfma_f32_16x16x32_bf16 v[12:15], v[218:221], v[190:193], v[12:15]
	v_mfma_f32_16x16x32_bf16 v[4:7], v[210:213], v[202:205], v[4:7]
	v_mfma_f32_16x16x32_bf16 v[0:3], v[218:221], v[202:205], v[0:3]
	s_setprio 0
	s_barrier
	ds_read_b128 v[146:149], v141
	ds_read_b128 v[150:153], v141 offset:1024
	ds_read_b128 v[160:163], v141 offset:2048
	ds_read_b128 v[166:169], v141 offset:3072
	s_add_u32 s24, s24, 0x80000
	s_addc_u32 s25, s25, 0
	s_mov_b32 m0, s54
	ds_read_b128 v[170:173], v139 offset:32768
	ds_read_b128 v[174:177], v139 offset:33792
	ds_read_b128 v[178:181], v139 offset:34816
	ds_read_b128 v[182:185], v139 offset:35840
	ds_read_b128 v[186:189], v139 offset:36864
	ds_read_b128 v[190:193], v139 offset:37888
	ds_read_b128 v[194:197], v139 offset:38912
	ds_read_b128 v[202:205], v139 offset:39936
	global_load_lds_dwordx4 v128, s[24:25]
	s_mov_b32 m0, s55
	s_nop 0
	global_load_lds_dwordx4 v130, s[24:25]
	s_waitcnt lgkmcnt(8)
	s_barrier
	s_waitcnt lgkmcnt(0)
	s_setprio 1
	s_waitcnt lgkmcnt(0)
	v_mfma_f32_16x16x32_bf16 v[124:127], v[146:149], v[170:173], v[124:127]
	v_mfma_f32_16x16x32_bf16 v[120:123], v[160:163], v[170:173], v[120:123]
	v_mfma_f32_16x16x32_bf16 v[112:115], v[146:149], v[178:181], v[112:115]
	v_mfma_f32_16x16x32_bf16 v[104:107], v[160:163], v[178:181], v[104:107]
	v_mfma_f32_16x16x32_bf16 v[96:99], v[146:149], v[186:189], v[96:99]
	v_mfma_f32_16x16x32_bf16 v[88:91], v[160:163], v[186:189], v[88:91]
	v_mfma_f32_16x16x32_bf16 v[80:83], v[146:149], v[194:197], v[80:83]
	v_mfma_f32_16x16x32_bf16 v[72:75], v[160:163], v[194:197], v[72:75]
	v_mfma_f32_16x16x32_bf16 v[124:127], v[150:153], v[174:177], v[124:127]
	v_mfma_f32_16x16x32_bf16 v[120:123], v[166:169], v[174:177], v[120:123]
	v_mfma_f32_16x16x32_bf16 v[112:115], v[150:153], v[182:185], v[112:115]
	v_mfma_f32_16x16x32_bf16 v[104:107], v[166:169], v[182:185], v[104:107]
	v_mfma_f32_16x16x32_bf16 v[96:99], v[150:153], v[190:193], v[96:99]
	v_mfma_f32_16x16x32_bf16 v[88:91], v[166:169], v[190:193], v[88:91]
	v_mfma_f32_16x16x32_bf16 v[80:83], v[150:153], v[202:205], v[80:83]
	v_mfma_f32_16x16x32_bf16 v[72:75], v[166:169], v[202:205], v[72:75]
	s_setprio 0
	s_barrier
	s_mov_b32 m0, s63
	ds_read_b128 v[206:209], v142
	ds_read_b128 v[210:213], v142 offset:1024
	ds_read_b128 v[214:217], v142 offset:2048
	ds_read_b128 v[218:221], v142 offset:3072
	global_load_lds_dwordx4 v144, s[98:99]
	s_mov_b32 m0, s64
	s_nop 0
	global_load_lds_dwordx4 v132, s[98:99]
	s_barrier
; #define PG8_STAGE(bufoff, gbase, voff) do { _Pragma("unroll") for (int _i = 0; _i < 2; ++_i) \
;         __builtin_amdgcn_global_load_lds((const unsigned*)((const char*)(gbase) + (voff)[_i]), (LAS unsigned*)(lds + (bufoff) + ldsw + _i * 8192), 16, 0, 0); } while (0)
; #define PG8_LDA(dst, b, h) do { _Pragma("unroll") for (int m = 0; m < 4; ++m) _Pragma("unroll") for (int k = 0; k < 2; ++k) dst[m][k] = *(const LAS bf16x8*)(lds + PG8_SA(b, h) + aoff + m * 2048 + k * 1024); } while (0)
; #define PG8_LDB(dst, b, h) do { _Pragma("unroll") for (int n = 0; n < 2; ++n) _Pragma("unroll") for (int k = 0; k < 2; ++k) dst[n][k] = *(const LAS bf16x8*)(lds + PG8_SB(b, h) + boff + n * 2048 + k * 1024); } while (0)
; #define PG8_WAIT_V(n) asm volatile("s_waitcnt vmcnt(" #n ")" ::: "memory")
; #define PG8_WAIT_L(n) asm volatile("s_waitcnt lgkmcnt(" #n ")" ::: "memory")
; #define PG8_BAR __builtin_amdgcn_s_barrier()
; #define PG8_SCHED __builtin_amdgcn_sched_barrier(0)
; template <class Epi>
; __device__ __forceinline__ void gemm_phase(LAS unsigned char* lds, const bf16_t* A, int lda, const bf16_t* Bt, int ldb, int M, int N, int K, int asel, const Epi& E, const int fixed_round = -1) {
;     ...
;             PG8_LDB(B0, 1, 0); PG8_SCHED; PG8_LDA(At, 1, 0); PG8_STAGE(PG8_SA(0, 1), a2 + hstepA, voffA);
;             PG8_WAIT_L(8); PG8_BAR; PG8_WAIT_L(0); PG8_MMA(0, 0, At, B0); PG8_BAR; PG8_SCHED;
;             PG8_LDB(B1, 1, 1); PG8_STAGE(PG8_SB(1, 0), b3, voffB);
;             PG8_BAR; PG8_WAIT_L(0); PG8_MMA(0, 1, At, B1); PG8_BAR;
;             PG8_LDA(At, 1, 1); PG8_STAGE(PG8_SA(1, 0), a3, voffA);
;             PG8_BAR; PG8_WAIT_L(0); PG8_MMA(1, 0, At, B0); PG8_BAR; PG8_SCHED;
;             PG8_STAGE(PG8_SB(1, 1), b3 + hstepB, voffB);
;             PG8_WAIT_V(6); PG8_BAR; PG8_MMA(1, 1, At, B1); PG8_BAR;
;     ...
;     PG8_WAIT_V(0);
;     if (wr == 0) PG8_BAR;
;     PG8_BAR;
	s_waitcnt lgkmcnt(0)
	s_setprio 1
	s_waitcnt lgkmcnt(0)
	v_mfma_f32_16x16x32_bf16 v[116:119], v[206:209], v[170:173], v[116:119]
	v_mfma_f32_16x16x32_bf16 v[108:111], v[214:217], v[170:173], v[108:111]
	v_mfma_f32_16x16x32_bf16 v[100:103], v[206:209], v[178:181], v[100:103]
	v_mfma_f32_16x16x32_bf16 v[92:95], v[214:217], v[178:181], v[92:95]
	v_mfma_f32_16x16x32_bf16 v[84:87], v[206:209], v[186:189], v[84:87]
	v_mfma_f32_16x16x32_bf16 v[76:79], v[214:217], v[186:189], v[76:79]
	v_mfma_f32_16x16x32_bf16 v[68:71], v[206:209], v[194:197], v[68:71]
	v_mfma_f32_16x16x32_bf16 v[64:67], v[214:217], v[194:197], v[64:67]
	v_mfma_f32_16x16x32_bf16 v[116:119], v[210:213], v[174:177], v[116:119]
	v_mfma_f32_16x16x32_bf16 v[108:111], v[218:221], v[174:177], v[108:111]
	v_mfma_f32_16x16x32_bf16 v[100:103], v[210:213], v[182:185], v[100:103]
	v_mfma_f32_16x16x32_bf16 v[92:95], v[218:221], v[182:185], v[92:95]
	v_mfma_f32_16x16x32_bf16 v[84:87], v[210:213], v[190:193], v[84:87]
	v_mfma_f32_16x16x32_bf16 v[76:79], v[218:221], v[190:193], v[76:79]
	v_mfma_f32_16x16x32_bf16 v[68:71], v[210:213], v[202:205], v[68:71]
	v_mfma_f32_16x16x32_bf16 v[64:67], v[218:221], v[202:205], v[64:67]
	s_setprio 0
	s_mov_b32 m0, s56
	s_barrier
	ds_read_b128 v[170:173], v139 offset:49152
	ds_read_b128 v[174:177], v139 offset:50176
	ds_read_b128 v[178:181], v139 offset:51200
	ds_read_b128 v[182:185], v139 offset:52224
	ds_read_b128 v[186:189], v139 offset:53248
	ds_read_b128 v[190:193], v139 offset:54272
	ds_read_b128 v[194:197], v139 offset:55296
	ds_read_b128 v[202:205], v139 offset:56320
	global_load_lds_dwordx4 v128, s[100:101]
	s_mov_b32 m0, s57
	s_nop 0
	global_load_lds_dwordx4 v130, s[100:101]
	s_barrier
	s_waitcnt lgkmcnt(0)
	s_setprio 1
	s_waitcnt lgkmcnt(0)
	v_mfma_f32_16x16x32_bf16 v[60:63], v[146:149], v[170:173], v[60:63]
	v_mfma_f32_16x16x32_bf16 v[56:59], v[160:163], v[170:173], v[56:59]
	v_mfma_f32_16x16x32_bf16 v[48:51], v[146:149], v[178:181], v[48:51]
	v_mfma_f32_16x16x32_bf16 v[40:43], v[160:163], v[178:181], v[40:43]
	v_mfma_f32_16x16x32_bf16 v[32:35], v[146:149], v[186:189], v[32:35]
	v_mfma_f32_16x16x32_bf16 v[24:27], v[160:163], v[186:189], v[24:27]
	v_mfma_f32_16x16x32_bf16 v[16:19], v[146:149], v[194:197], v[16:19]
	v_mfma_f32_16x16x32_bf16 v[8:11], v[160:163], v[194:197], v[8:11]
	v_mfma_f32_16x16x32_bf16 v[60:63], v[150:153], v[174:177], v[60:63]
	v_mfma_f32_16x16x32_bf16 v[56:59], v[166:169], v[174:177], v[56:59]
	v_mfma_f32_16x16x32_bf16 v[48:51], v[150:153], v[182:185], v[48:51]
	v_mfma_f32_16x16x32_bf16 v[40:43], v[166:169], v[182:185], v[40:43]
	v_mfma_f32_16x16x32_bf16 v[32:35], v[150:153], v[190:193], v[32:35]
	v_mfma_f32_16x16x32_bf16 v[24:27], v[166:169], v[190:193], v[24:27]
	v_mfma_f32_16x16x32_bf16 v[16:19], v[150:153], v[202:205], v[16:19]
	v_mfma_f32_16x16x32_bf16 v[8:11], v[166:169], v[202:205], v[8:11]
	s_setprio 0
	s_barrier
	s_add_u32 s22, s22, 0x80080
	s_addc_u32 s23, s23, 0
	s_mov_b32 m0, s65
	s_nop 0
	global_load_lds_dwordx4 v144, s[22:23]
	s_mov_b32 m0, s66
	s_nop 0
	global_load_lds_dwordx4 v132, s[22:23]
	s_waitcnt vmcnt(6)
	s_barrier
	s_setprio 1
	v_mfma_f32_16x16x32_bf16 v[52:55], v[206:209], v[170:173], v[52:55]
	v_mfma_f32_16x16x32_bf16 v[44:47], v[214:217], v[170:173], v[44:47]
	v_mfma_f32_16x16x32_bf16 v[36:39], v[206:209], v[178:181], v[36:39]
	v_mfma_f32_16x16x32_bf16 v[28:31], v[214:217], v[178:181], v[28:31]
	v_mfma_f32_16x16x32_bf16 v[20:23], v[206:209], v[186:189], v[20:23]
	v_mfma_f32_16x16x32_bf16 v[12:15], v[214:217], v[186:189], v[12:15]
	v_mfma_f32_16x16x32_bf16 v[4:7], v[206:209], v[194:197], v[4:7]
	v_mfma_f32_16x16x32_bf16 v[0:3], v[214:217], v[194:197], v[0:3]
	v_mfma_f32_16x16x32_bf16 v[52:55], v[210:213], v[174:177], v[52:55]
	v_mfma_f32_16x16x32_bf16 v[44:47], v[218:221], v[174:177], v[44:47]
	v_mfma_f32_16x16x32_bf16 v[36:39], v[210:213], v[182:185], v[36:39]
	v_mfma_f32_16x16x32_bf16 v[28:31], v[218:221], v[182:185], v[28:31]
	v_mfma_f32_16x16x32_bf16 v[20:23], v[210:213], v[190:193], v[20:23]
	v_mfma_f32_16x16x32_bf16 v[12:15], v[218:221], v[190:193], v[12:15]
	v_mfma_f32_16x16x32_bf16 v[4:7], v[210:213], v[202:205], v[4:7]
	v_mfma_f32_16x16x32_bf16 v[0:3], v[218:221], v[202:205], v[0:3]
	s_setprio 0
	s_add_i32 s40, s40, 2
	s_add_u32 s6, s6, 0x100
	s_addc_u32 s7, s7, 0
	s_cmp_lt_u32 s40, 30
	s_cbranch_scc1 .Lrot_9
	s_barrier
	s_waitcnt vmcnt(0)
	s_cmpk_gt_u32 s51, 0xff
	s_cbranch_scc1 .LBB0_1123
	s_barrier

; #define PG8_STAGE(bufoff, gbase, voff) do { _Pragma("unroll") for (int _i = 0; _i < 2; ++_i) \
;         __builtin_amdgcn_global_load_lds((const unsigned*)((const char*)(gbase) + (voff)[_i]), (LAS unsigned*)(lds + (bufoff) + ldsw + _i * 8192), 16, 0, 0); } while (0)
; #define PG8_LDA(dst, b, h) do { _Pragma("unroll") for (int m = 0; m < 4; ++m) _Pragma("unroll") for (int k = 0; k < 2; ++k) dst[m][k] = *(const LAS bf16x8*)(lds + PG8_SA(b, h) + aoff + m * 2048 + k * 1024); } while (0)
; #define PG8_LDB(dst, b, h) do { _Pragma("unroll") for (int n = 0; n < 2; ++n) _Pragma("unroll") for (int k = 0; k < 2; ++k) dst[n][k] = *(const LAS bf16x8*)(lds + PG8_SB(b, h) + boff + n * 2048 + k * 1024); } while (0)
; #define PG8_WAIT_L(n) asm volatile("s_waitcnt lgkmcnt(" #n ")" ::: "memory")
; #define PG8_BAR __builtin_amdgcn_s_barrier()
; #define PG8_SCHED __builtin_amdgcn_sched_barrier(0)
; template <class Epi>
; __device__ __forceinline__ void gemm_phase(LAS unsigned char* lds, const bf16_t* A, int lda, const bf16_t* Bt, int ldb, int M, int N, int K, int asel, const Epi& E, const int fixed_round = -1) {
;     ...
;         for (int t = 0; t < nt; t += 2) {
;             const bool last = (t == nt - 2);
;             const char* a1 = cA + (size_t)(t + 1) * kstep;
;             const char* a2 = last ? nA : cA + (size_t)(t + 2) * kstep; const char* b2 = last ? nB : cB + (size_t)(t + 2) * kstep;
;             const char* a3 = a2 + kstep; const char* b3 = b2 + kstep;
;             PG8_LDB(B0, 0, 0); PG8_SCHED; PG8_LDA(At, 0, 0); PG8_STAGE(PG8_SA(1, 1), a1 + hstepA, voffA);
;             PG8_WAIT_L(8); PG8_BAR; PG8_WAIT_L(0); PG8_MMA(0, 0, At, B0); PG8_BAR; PG8_SCHED;
;             PG8_LDB(B1, 0, 1); PG8_STAGE(PG8_SB(0, 0), b2, voffB);
;             PG8_BAR; PG8_WAIT_L(0); PG8_MMA(0, 1, At, B1); PG8_BAR;
;             PG8_LDA(At, 0, 1); PG8_STAGE(PG8_SA(0, 0), a2, voffA);
;             PG8_BAR; PG8_WAIT_L(0); PG8_MMA(1, 0, At, B0); PG8_BAR; PG8_SCHED;
;             PG8_STAGE(PG8_SB(0, 1), b2 + hstepB, voffB);
.LBB0_1283:
	ds_read_b128 v[146:149], v124
	ds_read_b128 v[150:153], v124 offset:1024
	ds_read_b128 v[154:157], v124 offset:2048
	ds_read_b128 v[158:161], v124 offset:3072
	s_mov_b32 m0, s47
	v_lshl_add_u64 v[194:195], v[120:121], 0, s[22:23]
	ds_read_b128 v[162:165], v125
	ds_read_b128 v[166:169], v125 offset:1024
	ds_read_b128 v[170:173], v125 offset:2048
	ds_read_b128 v[174:177], v125 offset:3072
	ds_read_b128 v[178:181], v125 offset:4096
	ds_read_b128 v[182:185], v125 offset:5120
	ds_read_b128 v[186:189], v125 offset:6144
	ds_read_b128 v[190:193], v125 offset:7168
	global_load_lds_dwordx4 v[194:195], off
	v_lshl_add_u64 v[194:195], v[122:123], 0, s[22:23]
	s_mov_b32 m0, s48
	s_nop 0
	global_load_lds_dwordx4 v[194:195], off
	s_waitcnt lgkmcnt(8)
	s_barrier
	s_waitcnt lgkmcnt(0)
	s_setprio 1
	s_waitcnt lgkmcnt(0)
	v_mfma_f32_16x16x32_bf16 v[140:143], v[146:149], v[162:165], v[140:143]
	v_mfma_f32_16x16x32_bf16 v[136:139], v[154:157], v[162:165], v[136:139]
	v_mfma_f32_16x16x32_bf16 v[108:111], v[146:149], v[170:173], v[108:111]
	v_mfma_f32_16x16x32_bf16 v[104:107], v[154:157], v[170:173], v[104:107]
	v_mfma_f32_16x16x32_bf16 v[92:95], v[146:149], v[178:181], v[92:95]
	v_mfma_f32_16x16x32_bf16 v[88:91], v[154:157], v[178:181], v[88:91]
	v_mfma_f32_16x16x32_bf16 v[76:79], v[146:149], v[186:189], v[76:79]
	v_mfma_f32_16x16x32_bf16 v[72:75], v[154:157], v[186:189], v[72:75]
	v_mfma_f32_16x16x32_bf16 v[140:143], v[150:153], v[166:169], v[140:143]
	v_mfma_f32_16x16x32_bf16 v[136:139], v[158:161], v[166:169], v[136:139]
	v_mfma_f32_16x16x32_bf16 v[108:111], v[150:153], v[174:177], v[108:111]
	v_mfma_f32_16x16x32_bf16 v[104:107], v[158:161], v[174:177], v[104:107]
	v_mfma_f32_16x16x32_bf16 v[92:95], v[150:153], v[182:185], v[92:95]
	v_mfma_f32_16x16x32_bf16 v[88:91], v[158:161], v[182:185], v[88:91]
	v_mfma_f32_16x16x32_bf16 v[76:79], v[150:153], v[190:193], v[76:79]
	v_mfma_f32_16x16x32_bf16 v[72:75], v[158:161], v[190:193], v[72:75]
	s_setprio 0
	s_barrier
	s_add_u32 s24, s16, s22
	s_addc_u32 s25, s17, s23
	s_add_u32 s24, s24, 0x18500100
	s_addc_u32 s25, s25, 0
	s_add_u32 s57, s28, s22
	s_addc_u32 s58, s29, s23
	s_cmpk_eq_i32 s22, 0x3f00
	s_cselect_b32 s27, s87, s25
	s_cselect_b32 s26, s86, s24
	s_cselect_b32 s25, s3, s58
	s_cselect_b32 s24, s2, s57
	s_mov_b32 m0, s49
	s_add_u32 s98, s24, s0
	s_addc_u32 s99, s25, s1
	ds_read_b128 v[194:197], v126
	ds_read_b128 v[204:207], v126 offset:1024
	ds_read_b128 v[208:211], v126 offset:2048
	ds_read_b128 v[212:215], v126 offset:3072
	global_load_lds_dwordx4 v114, s[24:25]
	s_mov_b32 m0, s50
	s_nop 0
	global_load_lds_dwordx4 v118, s[24:25]
	s_barrier
	s_waitcnt lgkmcnt(0)
	s_setprio 1
	s_waitcnt lgkmcnt(0)
	v_mfma_f32_16x16x32_bf16 v[132:135], v[194:197], v[162:165], v[132:135]
	v_mfma_f32_16x16x32_bf16 v[128:131], v[208:211], v[162:165], v[128:131]
	v_mfma_f32_16x16x32_bf16 v[100:103], v[194:197], v[170:173], v[100:103]
	v_mfma_f32_16x16x32_bf16 v[96:99], v[208:211], v[170:173], v[96:99]
	v_mfma_f32_16x16x32_bf16 v[84:87], v[194:197], v[178:181], v[84:87]
	v_mfma_f32_16x16x32_bf16 v[80:83], v[208:211], v[178:181], v[80:83]
	v_mfma_f32_16x16x32_bf16 v[68:71], v[194:197], v[186:189], v[68:71]
	v_mfma_f32_16x16x32_bf16 v[64:67], v[208:211], v[186:189], v[64:67]
	v_mfma_f32_16x16x32_bf16 v[132:135], v[204:207], v[166:169], v[132:135]
	v_mfma_f32_16x16x32_bf16 v[128:131], v[212:215], v[166:169], v[128:131]
	v_mfma_f32_16x16x32_bf16 v[100:103], v[204:207], v[174:177], v[100:103]
	v_mfma_f32_16x16x32_bf16 v[96:99], v[212:215], v[174:177], v[96:99]
	v_mfma_f32_16x16x32_bf16 v[84:87], v[204:207], v[182:185], v[84:87]
	v_mfma_f32_16x16x32_bf16 v[80:83], v[212:215], v[182:185], v[80:83]
	v_mfma_f32_16x16x32_bf16 v[68:71], v[204:207], v[190:193], v[68:71]
	v_mfma_f32_16x16x32_bf16 v[64:67], v[212:215], v[190:193], v[64:67]
	s_setprio 0
	s_mov_b32 m0, s40
	s_add_u32 s100, s26, s0
	s_addc_u32 s101, s27, s1
	s_barrier
	ds_read_b128 v[162:165], v125 offset:16384
	ds_read_b128 v[166:169], v125 offset:17408
	ds_read_b128 v[170:173], v125 offset:18432
	ds_read_b128 v[174:177], v125 offset:19456
	ds_read_b128 v[178:181], v125 offset:20480
	ds_read_b128 v[182:185], v125 offset:21504
	ds_read_b128 v[186:189], v125 offset:22528
	ds_read_b128 v[190:193], v125 offset:23552
	global_load_lds_dwordx4 v112, s[26:27]
	s_mov_b32 m0, s41
	s_nop 0
	global_load_lds_dwordx4 v116, s[26:27]
	s_barrier
	s_waitcnt lgkmcnt(0)
	s_setprio 1
	s_waitcnt lgkmcnt(0)
	v_mfma_f32_16x16x32_bf16 v[60:63], v[146:149], v[162:165], v[60:63]
	v_mfma_f32_16x16x32_bf16 v[56:59], v[154:157], v[162:165], v[56:59]
	v_mfma_f32_16x16x32_bf16 v[44:47], v[146:149], v[170:173], v[44:47]
	v_mfma_f32_16x16x32_bf16 v[40:43], v[154:157], v[170:173], v[40:43]
	v_mfma_f32_16x16x32_bf16 v[28:31], v[146:149], v[178:181], v[28:31]
	v_mfma_f32_16x16x32_bf16 v[24:27], v[154:157], v[178:181], v[24:27]
	v_mfma_f32_16x16x32_bf16 v[12:15], v[146:149], v[186:189], v[12:15]
	v_mfma_f32_16x16x32_bf16 v[8:11], v[154:157], v[186:189], v[8:11]
	v_mfma_f32_16x16x32_bf16 v[60:63], v[150:153], v[166:169], v[60:63]
	v_mfma_f32_16x16x32_bf16 v[56:59], v[158:161], v[166:169], v[56:59]
	v_mfma_f32_16x16x32_bf16 v[44:47], v[150:153], v[174:177], v[44:47]
	v_mfma_f32_16x16x32_bf16 v[40:43], v[158:161], v[174:177], v[40:43]
	v_mfma_f32_16x16x32_bf16 v[28:31], v[150:153], v[182:185], v[28:31]
	v_mfma_f32_16x16x32_bf16 v[24:27], v[158:161], v[182:185], v[24:27]
	v_mfma_f32_16x16x32_bf16 v[12:15], v[150:153], v[190:193], v[12:15]
	v_mfma_f32_16x16x32_bf16 v[8:11], v[158:161], v[190:193], v[8:11]
	s_setprio 0
	s_barrier
; #define PG8_STAGE(bufoff, gbase, voff) do { _Pragma("unroll") for (int _i = 0; _i < 2; ++_i) \
;         __builtin_amdgcn_global_load_lds((const unsigned*)((const char*)(gbase) + (voff)[_i]), (LAS unsigned*)(lds + (bufoff) + ldsw + _i * 8192), 16, 0, 0); } while (0)
; #define PG8_LDA(dst, b, h) do { _Pragma("unroll") for (int m = 0; m < 4; ++m) _Pragma("unroll") for (int k = 0; k < 2; ++k) dst[m][k] = *(const LAS bf16x8*)(lds + PG8_SA(b, h) + aoff + m * 2048 + k * 1024); } while (0)
; #define PG8_LDB(dst, b, h) do { _Pragma("unroll") for (int n = 0; n < 2; ++n) _Pragma("unroll") for (int k = 0; k < 2; ++k) dst[n][k] = *(const LAS bf16x8*)(lds + PG8_SB(b, h) + boff + n * 2048 + k * 1024); } while (0)
; #define PG8_WAIT_V(n) asm volatile("s_waitcnt vmcnt(" #n ")" ::: "memory")
; #define PG8_WAIT_L(n) asm volatile("s_waitcnt lgkmcnt(" #n ")" ::: "memory")
; #define PG8_BAR __builtin_amdgcn_s_barrier()
; #define PG8_SCHED __builtin_amdgcn_sched_barrier(0)
; template <class Epi>
; __device__ __forceinline__ void gemm_phase(LAS unsigned char* lds, const bf16_t* A, int lda, const bf16_t* Bt, int ldb, int M, int N, int K, int asel, const Epi& E, const int fixed_round = -1) {
;     ...
;             PG8_STAGE(PG8_SB(0, 1), b2 + hstepB, voffB);
;             PG8_WAIT_V(6); PG8_BAR; PG8_MMA(1, 1, At, B1); PG8_BAR;
;             PG8_LDB(B0, 1, 0); PG8_SCHED; PG8_LDA(At, 1, 0); PG8_STAGE(PG8_SA(0, 1), a2 + hstepA, voffA);
;             PG8_WAIT_L(8); PG8_BAR; PG8_WAIT_L(0); PG8_MMA(0, 0, At, B0); PG8_BAR; PG8_SCHED;
;             PG8_LDB(B1, 1, 1); PG8_STAGE(PG8_SB(1, 0), b3, voffB);
	s_add_u32 s58, s24, 0x200000
	s_addc_u32 s59, s25, 0
	s_mov_b32 m0, s51
	s_nop 0
	global_load_lds_dwordx4 v114, s[58:59]
	s_mov_b32 m0, s52
	s_nop 0
	global_load_lds_dwordx4 v118, s[58:59]
	s_waitcnt vmcnt(6)
	s_barrier
	s_setprio 1
	v_mfma_f32_16x16x32_bf16 v[52:55], v[194:197], v[162:165], v[52:55]
	v_mfma_f32_16x16x32_bf16 v[48:51], v[208:211], v[162:165], v[48:51]
	v_mfma_f32_16x16x32_bf16 v[36:39], v[194:197], v[170:173], v[36:39]
	v_mfma_f32_16x16x32_bf16 v[32:35], v[208:211], v[170:173], v[32:35]
	v_mfma_f32_16x16x32_bf16 v[20:23], v[194:197], v[178:181], v[20:23]
	v_mfma_f32_16x16x32_bf16 v[16:19], v[208:211], v[178:181], v[16:19]
	v_mfma_f32_16x16x32_bf16 v[4:7], v[194:197], v[186:189], v[4:7]
	v_mfma_f32_16x16x32_bf16 v[0:3], v[208:211], v[186:189], v[0:3]
	v_mfma_f32_16x16x32_bf16 v[52:55], v[204:207], v[166:169], v[52:55]
	v_mfma_f32_16x16x32_bf16 v[48:51], v[212:215], v[166:169], v[48:51]
	v_mfma_f32_16x16x32_bf16 v[36:39], v[204:207], v[174:177], v[36:39]
	v_mfma_f32_16x16x32_bf16 v[32:35], v[212:215], v[174:177], v[32:35]
	v_mfma_f32_16x16x32_bf16 v[20:23], v[204:207], v[182:185], v[20:23]
	v_mfma_f32_16x16x32_bf16 v[16:19], v[212:215], v[182:185], v[16:19]
	v_mfma_f32_16x16x32_bf16 v[4:7], v[204:207], v[190:193], v[4:7]
	v_mfma_f32_16x16x32_bf16 v[0:3], v[212:215], v[190:193], v[0:3]
	s_setprio 0
	s_barrier
	ds_read_b128 v[146:149], v127
	ds_read_b128 v[150:153], v127 offset:1024
	ds_read_b128 v[154:157], v127 offset:2048
	ds_read_b128 v[158:161], v127 offset:3072
	s_add_u32 s26, s26, 0x200000
	s_addc_u32 s27, s27, 0
	s_mov_b32 m0, s42
	ds_read_b128 v[162:165], v125 offset:32768
	ds_read_b128 v[166:169], v125 offset:33792
	ds_read_b128 v[170:173], v125 offset:34816
	ds_read_b128 v[174:177], v125 offset:35840
	ds_read_b128 v[178:181], v125 offset:36864
	ds_read_b128 v[182:185], v125 offset:37888
	ds_read_b128 v[186:189], v125 offset:38912
	ds_read_b128 v[190:193], v125 offset:39936
	global_load_lds_dwordx4 v112, s[26:27]
	s_mov_b32 m0, s43
	s_nop 0
	global_load_lds_dwordx4 v116, s[26:27]
	s_waitcnt lgkmcnt(8)
	s_barrier
	s_waitcnt lgkmcnt(0)
	s_setprio 1
	s_waitcnt lgkmcnt(0)
	v_mfma_f32_16x16x32_bf16 v[140:143], v[146:149], v[162:165], v[140:143]
	v_mfma_f32_16x16x32_bf16 v[136:139], v[154:157], v[162:165], v[136:139]
	v_mfma_f32_16x16x32_bf16 v[108:111], v[146:149], v[170:173], v[108:111]
	v_mfma_f32_16x16x32_bf16 v[104:107], v[154:157], v[170:173], v[104:107]
	v_mfma_f32_16x16x32_bf16 v[92:95], v[146:149], v[178:181], v[92:95]
	v_mfma_f32_16x16x32_bf16 v[88:91], v[154:157], v[178:181], v[88:91]
	v_mfma_f32_16x16x32_bf16 v[76:79], v[146:149], v[186:189], v[76:79]
	v_mfma_f32_16x16x32_bf16 v[72:75], v[154:157], v[186:189], v[72:75]
	v_mfma_f32_16x16x32_bf16 v[140:143], v[150:153], v[166:169], v[140:143]
	v_mfma_f32_16x16x32_bf16 v[136:139], v[158:161], v[166:169], v[136:139]
	v_mfma_f32_16x16x32_bf16 v[108:111], v[150:153], v[174:177], v[108:111]
	v_mfma_f32_16x16x32_bf16 v[104:107], v[158:161], v[174:177], v[104:107]
	v_mfma_f32_16x16x32_bf16 v[92:95], v[150:153], v[182:185], v[92:95]
	v_mfma_f32_16x16x32_bf16 v[88:91], v[158:161], v[182:185], v[88:91]
	v_mfma_f32_16x16x32_bf16 v[76:79], v[150:153], v[190:193], v[76:79]
	v_mfma_f32_16x16x32_bf16 v[72:75], v[158:161], v[190:193], v[72:75]
	s_setprio 0
	s_barrier
	s_mov_b32 m0, s53
	ds_read_b128 v[194:197], v144
	ds_read_b128 v[204:207], v144 offset:1024
	ds_read_b128 v[208:211], v144 offset:2048
	ds_read_b128 v[212:215], v144 offset:3072
	global_load_lds_dwordx4 v114, s[98:99]
	s_mov_b32 m0, s54
	s_nop 0
	global_load_lds_dwordx4 v118, s[98:99]
	s_barrier
; #define PG8_STAGE(bufoff, gbase, voff) do { _Pragma("unroll") for (int _i = 0; _i < 2; ++_i) \
;         __builtin_amdgcn_global_load_lds((const unsigned*)((const char*)(gbase) + (voff)[_i]), (LAS unsigned*)(lds + (bufoff) + ldsw + _i * 8192), 16, 0, 0); } while (0)
; #define PG8_LDA(dst, b, h) do { _Pragma("unroll") for (int m = 0; m < 4; ++m) _Pragma("unroll") for (int k = 0; k < 2; ++k) dst[m][k] = *(const LAS bf16x8*)(lds + PG8_SA(b, h) + aoff + m * 2048 + k * 1024); } while (0)
; #define PG8_WAIT_V(n) asm volatile("s_waitcnt vmcnt(" #n ")" ::: "memory")
; #define PG8_WAIT_L(n) asm volatile("s_waitcnt lgkmcnt(" #n ")" ::: "memory")
; #define PG8_BAR __builtin_amdgcn_s_barrier()
; #define PG8_SCHED __builtin_amdgcn_sched_barrier(0)
; template <class Epi>
; __device__ __forceinline__ void gemm_phase(LAS unsigned char* lds, const bf16_t* A, int lda, const bf16_t* Bt, int ldb, int M, int N, int K, int asel, const Epi& E, const int fixed_round = -1) {
;     ...
;             PG8_BAR; PG8_WAIT_L(0); PG8_MMA(0, 1, At, B1); PG8_BAR;
;             PG8_LDA(At, 1, 1); PG8_STAGE(PG8_SA(1, 0), a3, voffA);
;             PG8_BAR; PG8_WAIT_L(0); PG8_MMA(1, 0, At, B0); PG8_BAR; PG8_SCHED;
;             PG8_STAGE(PG8_SB(1, 1), b3 + hstepB, voffB);
;             PG8_WAIT_V(6); PG8_BAR; PG8_MMA(1, 1, At, B1); PG8_BAR;
;     ...
;     PG8_WAIT_V(0);
;     if (wr == 0) PG8_BAR;
;     PG8_BAR;
	s_waitcnt lgkmcnt(0)
	s_setprio 1
	s_waitcnt lgkmcnt(0)
	v_mfma_f32_16x16x32_bf16 v[132:135], v[194:197], v[162:165], v[132:135]
	v_mfma_f32_16x16x32_bf16 v[128:131], v[208:211], v[162:165], v[128:131]
	v_mfma_f32_16x16x32_bf16 v[100:103], v[194:197], v[170:173], v[100:103]
	v_mfma_f32_16x16x32_bf16 v[96:99], v[208:211], v[170:173], v[96:99]
	v_mfma_f32_16x16x32_bf16 v[84:87], v[194:197], v[178:181], v[84:87]
	v_mfma_f32_16x16x32_bf16 v[80:83], v[208:211], v[178:181], v[80:83]
	v_mfma_f32_16x16x32_bf16 v[68:71], v[194:197], v[186:189], v[68:71]
	v_mfma_f32_16x16x32_bf16 v[64:67], v[208:211], v[186:189], v[64:67]
	v_mfma_f32_16x16x32_bf16 v[132:135], v[204:207], v[166:169], v[132:135]
	v_mfma_f32_16x16x32_bf16 v[128:131], v[212:215], v[166:169], v[128:131]
	v_mfma_f32_16x16x32_bf16 v[100:103], v[204:207], v[174:177], v[100:103]
	v_mfma_f32_16x16x32_bf16 v[96:99], v[212:215], v[174:177], v[96:99]
	v_mfma_f32_16x16x32_bf16 v[84:87], v[204:207], v[182:185], v[84:87]
	v_mfma_f32_16x16x32_bf16 v[80:83], v[212:215], v[182:185], v[80:83]
	v_mfma_f32_16x16x32_bf16 v[68:71], v[204:207], v[190:193], v[68:71]
	v_mfma_f32_16x16x32_bf16 v[64:67], v[212:215], v[190:193], v[64:67]
	s_setprio 0
	s_mov_b32 m0, s44
	s_barrier
	ds_read_b128 v[162:165], v125 offset:49152
	ds_read_b128 v[166:169], v125 offset:50176
	ds_read_b128 v[170:173], v125 offset:51200
	ds_read_b128 v[174:177], v125 offset:52224
	ds_read_b128 v[178:181], v125 offset:53248
	ds_read_b128 v[182:185], v125 offset:54272
	ds_read_b128 v[186:189], v125 offset:55296
	ds_read_b128 v[190:193], v125 offset:56320
	global_load_lds_dwordx4 v112, s[100:101]
	s_mov_b32 m0, s45
	s_nop 0
	global_load_lds_dwordx4 v116, s[100:101]
	s_barrier
	s_waitcnt lgkmcnt(0)
	s_setprio 1
	s_waitcnt lgkmcnt(0)
	v_mfma_f32_16x16x32_bf16 v[60:63], v[146:149], v[162:165], v[60:63]
	v_mfma_f32_16x16x32_bf16 v[56:59], v[154:157], v[162:165], v[56:59]
	v_mfma_f32_16x16x32_bf16 v[44:47], v[146:149], v[170:173], v[44:47]
	v_mfma_f32_16x16x32_bf16 v[40:43], v[154:157], v[170:173], v[40:43]
	v_mfma_f32_16x16x32_bf16 v[28:31], v[146:149], v[178:181], v[28:31]
	v_mfma_f32_16x16x32_bf16 v[24:27], v[154:157], v[178:181], v[24:27]
	v_mfma_f32_16x16x32_bf16 v[12:15], v[146:149], v[186:189], v[12:15]
	v_mfma_f32_16x16x32_bf16 v[8:11], v[154:157], v[186:189], v[8:11]
	v_mfma_f32_16x16x32_bf16 v[60:63], v[150:153], v[166:169], v[60:63]
	v_mfma_f32_16x16x32_bf16 v[56:59], v[158:161], v[166:169], v[56:59]
	v_mfma_f32_16x16x32_bf16 v[44:47], v[150:153], v[174:177], v[44:47]
	v_mfma_f32_16x16x32_bf16 v[40:43], v[158:161], v[174:177], v[40:43]
	v_mfma_f32_16x16x32_bf16 v[28:31], v[150:153], v[182:185], v[28:31]
	v_mfma_f32_16x16x32_bf16 v[24:27], v[158:161], v[182:185], v[24:27]
	v_mfma_f32_16x16x32_bf16 v[12:15], v[150:153], v[190:193], v[12:15]
	v_mfma_f32_16x16x32_bf16 v[8:11], v[158:161], v[190:193], v[8:11]
	s_setprio 0
	s_barrier
	s_add_u32 s24, s24, 0x200080
	s_addc_u32 s25, s25, 0
	s_mov_b32 m0, s55
	s_nop 0
	global_load_lds_dwordx4 v114, s[24:25]
	s_mov_b32 m0, s56
	s_nop 0
	global_load_lds_dwordx4 v118, s[24:25]
	s_waitcnt vmcnt(6)
	s_barrier
	s_setprio 1
	v_mfma_f32_16x16x32_bf16 v[52:55], v[194:197], v[162:165], v[52:55]
	v_mfma_f32_16x16x32_bf16 v[48:51], v[208:211], v[162:165], v[48:51]
	v_mfma_f32_16x16x32_bf16 v[36:39], v[194:197], v[170:173], v[36:39]
	v_mfma_f32_16x16x32_bf16 v[32:35], v[208:211], v[170:173], v[32:35]
	v_mfma_f32_16x16x32_bf16 v[20:23], v[194:197], v[178:181], v[20:23]
	v_mfma_f32_16x16x32_bf16 v[16:19], v[208:211], v[178:181], v[16:19]
	v_mfma_f32_16x16x32_bf16 v[4:7], v[194:197], v[186:189], v[4:7]
	v_mfma_f32_16x16x32_bf16 v[0:3], v[208:211], v[186:189], v[0:3]
	v_mfma_f32_16x16x32_bf16 v[52:55], v[204:207], v[166:169], v[52:55]
	v_mfma_f32_16x16x32_bf16 v[48:51], v[212:215], v[166:169], v[48:51]
	v_mfma_f32_16x16x32_bf16 v[36:39], v[204:207], v[174:177], v[36:39]
	v_mfma_f32_16x16x32_bf16 v[32:35], v[212:215], v[174:177], v[32:35]
	v_mfma_f32_16x16x32_bf16 v[20:23], v[204:207], v[182:185], v[20:23]
	v_mfma_f32_16x16x32_bf16 v[16:19], v[212:215], v[182:185], v[16:19]
	v_mfma_f32_16x16x32_bf16 v[4:7], v[204:207], v[190:193], v[4:7]
	v_mfma_f32_16x16x32_bf16 v[0:3], v[212:215], v[190:193], v[0:3]
	s_setprio 0
	s_add_i32 s46, s46, 2
	s_add_u32 s22, s22, 0x100
	s_addc_u32 s23, s23, 0
	s_cmpk_lt_u32 s46, 0x7e
	s_cbranch_scc1 .Lrot_11
	s_barrier
	s_waitcnt vmcnt(0)
	v_readlane_b32 s48, v254, 0
	s_cmpk_gt_u32 s33, 0xff
	v_readlane_b32 s54, v254, 6
	v_readlane_b32 s55, v254, 7
	v_readlane_b32 s49, v254, 1
	v_readlane_b32 s50, v254, 2
	v_readlane_b32 s51, v254, 3
	v_readlane_b32 s52, v254, 4
	v_readlane_b32 s53, v254, 5
	s_cbranch_scc1 .LBB0_1286
	s_barrier

; #define PG8_STAGE(bufoff, gbase, voff) do { _Pragma("unroll") for (int _i = 0; _i < 2; ++_i) \
;         __builtin_amdgcn_global_load_lds((const unsigned*)((const char*)(gbase) + (voff)[_i]), (LAS unsigned*)(lds + (bufoff) + ldsw + _i * 8192), 16, 0, 0); } while (0)
; #define PG8_LDA(dst, b, h) do { _Pragma("unroll") for (int m = 0; m < 4; ++m) _Pragma("unroll") for (int k = 0; k < 2; ++k) dst[m][k] = *(const LAS bf16x8*)(lds + PG8_SA(b, h) + aoff + m * 2048 + k * 1024); } while (0)
; #define PG8_LDB(dst, b, h) do { _Pragma("unroll") for (int n = 0; n < 2; ++n) _Pragma("unroll") for (int k = 0; k < 2; ++k) dst[n][k] = *(const LAS bf16x8*)(lds + PG8_SB(b, h) + boff + n * 2048 + k * 1024); } while (0)
; #define PG8_WAIT_L(n) asm volatile("s_waitcnt lgkmcnt(" #n ")" ::: "memory")
; #define PG8_BAR __builtin_amdgcn_s_barrier()
; #define PG8_SCHED __builtin_amdgcn_sched_barrier(0)
; template <class Epi>
; __device__ __forceinline__ void gemm_phase(LAS unsigned char* lds, const bf16_t* A, int lda, const bf16_t* Bt, int ldb, int M, int N, int K, int asel, const Epi& E, const int fixed_round = -1) {
;     ...
;         for (int t = 0; t < nt; t += 2) {
;             const bool last = (t == nt - 2);
;             const char* a1 = cA + (size_t)(t + 1) * kstep;
;             const char* a2 = last ? nA : cA + (size_t)(t + 2) * kstep; const char* b2 = last ? nB : cB + (size_t)(t + 2) * kstep;
;             const char* a3 = a2 + kstep; const char* b3 = b2 + kstep;
;             PG8_LDB(B0, 0, 0); PG8_SCHED; PG8_LDA(At, 0, 0); PG8_STAGE(PG8_SA(1, 1), a1 + hstepA, voffA);
;             PG8_WAIT_L(8); PG8_BAR; PG8_WAIT_L(0); PG8_MMA(0, 0, At, B0); PG8_BAR; PG8_SCHED;
;             PG8_LDB(B1, 0, 1); PG8_STAGE(PG8_SB(0, 0), b2, voffB);
;             PG8_BAR; PG8_WAIT_L(0); PG8_MMA(0, 1, At, B1); PG8_BAR;
;             PG8_LDA(At, 0, 1); PG8_STAGE(PG8_SA(0, 0), a2, voffA);
;             PG8_BAR; PG8_WAIT_L(0); PG8_MMA(1, 0, At, B0); PG8_BAR; PG8_SCHED;
;             PG8_STAGE(PG8_SB(0, 1), b2 + hstepB, voffB);
.LBB0_1322:
	ds_read_b128 v[144:147], v122
	ds_read_b128 v[148:151], v122 offset:1024
	ds_read_b128 v[152:155], v122 offset:2048
	ds_read_b128 v[156:159], v122 offset:3072
	s_mov_b32 m0, s35
	v_lshl_add_u64 v[192:193], v[118:119], 0, s[6:7]
	ds_read_b128 v[160:163], v123
	ds_read_b128 v[164:167], v123 offset:1024
	ds_read_b128 v[168:171], v123 offset:2048
	ds_read_b128 v[172:175], v123 offset:3072
	ds_read_b128 v[176:179], v123 offset:4096
	ds_read_b128 v[180:183], v123 offset:5120
	ds_read_b128 v[184:187], v123 offset:6144
	ds_read_b128 v[188:191], v123 offset:7168
	global_load_lds_dwordx4 v[192:193], off
	v_lshl_add_u64 v[192:193], v[120:121], 0, s[6:7]
	s_mov_b32 m0, s40
	s_nop 0
	global_load_lds_dwordx4 v[192:193], off
	s_waitcnt lgkmcnt(8)
	s_barrier
	s_waitcnt lgkmcnt(0)
	s_setprio 1
	s_waitcnt lgkmcnt(0)
	v_mfma_f32_16x16x32_bf16 v[140:143], v[144:147], v[160:163], v[140:143]
	v_mfma_f32_16x16x32_bf16 v[136:139], v[152:155], v[160:163], v[136:139]
	v_mfma_f32_16x16x32_bf16 v[108:111], v[144:147], v[168:171], v[108:111]
	v_mfma_f32_16x16x32_bf16 v[104:107], v[152:155], v[168:171], v[104:107]
	v_mfma_f32_16x16x32_bf16 v[92:95], v[144:147], v[176:179], v[92:95]
	v_mfma_f32_16x16x32_bf16 v[88:91], v[152:155], v[176:179], v[88:91]
	v_mfma_f32_16x16x32_bf16 v[76:79], v[144:147], v[184:187], v[76:79]
	v_mfma_f32_16x16x32_bf16 v[72:75], v[152:155], v[184:187], v[72:75]
	v_mfma_f32_16x16x32_bf16 v[140:143], v[148:151], v[164:167], v[140:143]
	v_mfma_f32_16x16x32_bf16 v[136:139], v[156:159], v[164:167], v[136:139]
	v_mfma_f32_16x16x32_bf16 v[108:111], v[148:151], v[172:175], v[108:111]
	v_mfma_f32_16x16x32_bf16 v[104:107], v[156:159], v[172:175], v[104:107]
	v_mfma_f32_16x16x32_bf16 v[92:95], v[148:151], v[180:183], v[92:95]
	v_mfma_f32_16x16x32_bf16 v[88:91], v[156:159], v[180:183], v[88:91]
	v_mfma_f32_16x16x32_bf16 v[76:79], v[148:151], v[188:191], v[76:79]
	v_mfma_f32_16x16x32_bf16 v[72:75], v[156:159], v[188:191], v[72:75]
	s_setprio 0
	s_barrier
	s_add_u32 s8, s4, s6
	s_addc_u32 s9, s5, s7
	s_add_u32 s8, s8, 0x18500100
	s_addc_u32 s9, s9, 0
	s_add_u32 s49, s28, s6
	s_addc_u32 s50, s29, s7
	s_cmpk_eq_i32 s6, 0x3f00
	s_cselect_b32 s13, s11, s9
	s_cselect_b32 s12, s10, s8
	s_cselect_b32 s9, s3, s50
	s_cselect_b32 s8, s2, s49
	s_mov_b32 m0, s41
	s_add_u32 s98, s8, s0
	s_addc_u32 s99, s9, s1
	ds_read_b128 v[192:195], v124
	ds_read_b128 v[196:199], v124 offset:1024
	ds_read_b128 v[204:207], v124 offset:2048
	ds_read_b128 v[208:211], v124 offset:3072
	global_load_lds_dwordx4 v202, s[8:9]
	s_mov_b32 m0, s42
	s_nop 0
	global_load_lds_dwordx4 v116, s[8:9]
	s_barrier
	s_waitcnt lgkmcnt(0)
	s_setprio 1
	s_waitcnt lgkmcnt(0)
	v_mfma_f32_16x16x32_bf16 v[132:135], v[192:195], v[160:163], v[132:135]
	v_mfma_f32_16x16x32_bf16 v[128:131], v[204:207], v[160:163], v[128:131]
	v_mfma_f32_16x16x32_bf16 v[100:103], v[192:195], v[168:171], v[100:103]
	v_mfma_f32_16x16x32_bf16 v[96:99], v[204:207], v[168:171], v[96:99]
	v_mfma_f32_16x16x32_bf16 v[84:87], v[192:195], v[176:179], v[84:87]
	v_mfma_f32_16x16x32_bf16 v[80:83], v[204:207], v[176:179], v[80:83]
	v_mfma_f32_16x16x32_bf16 v[68:71], v[192:195], v[184:187], v[68:71]
	v_mfma_f32_16x16x32_bf16 v[64:67], v[204:207], v[184:187], v[64:67]
	v_mfma_f32_16x16x32_bf16 v[132:135], v[196:199], v[164:167], v[132:135]
	v_mfma_f32_16x16x32_bf16 v[128:131], v[208:211], v[164:167], v[128:131]
	v_mfma_f32_16x16x32_bf16 v[100:103], v[196:199], v[172:175], v[100:103]
	v_mfma_f32_16x16x32_bf16 v[96:99], v[208:211], v[172:175], v[96:99]
	v_mfma_f32_16x16x32_bf16 v[84:87], v[196:199], v[180:183], v[84:87]
	v_mfma_f32_16x16x32_bf16 v[80:83], v[208:211], v[180:183], v[80:83]
	v_mfma_f32_16x16x32_bf16 v[68:71], v[196:199], v[188:191], v[68:71]
	v_mfma_f32_16x16x32_bf16 v[64:67], v[208:211], v[188:191], v[64:67]
	s_setprio 0
	s_mov_b32 m0, s19
	s_add_u32 s100, s12, s0
	s_addc_u32 s101, s13, s1
	s_barrier
	ds_read_b128 v[160:163], v123 offset:16384
	ds_read_b128 v[164:167], v123 offset:17408
	ds_read_b128 v[168:171], v123 offset:18432
	ds_read_b128 v[172:175], v123 offset:19456
	ds_read_b128 v[176:179], v123 offset:20480
	ds_read_b128 v[180:183], v123 offset:21504
	ds_read_b128 v[184:187], v123 offset:22528
	ds_read_b128 v[188:191], v123 offset:23552
	global_load_lds_dwordx4 v112, s[12:13]
	s_mov_b32 m0, s30
	s_nop 0
	global_load_lds_dwordx4 v114, s[12:13]
	s_barrier
	s_waitcnt lgkmcnt(0)
	s_setprio 1
	s_waitcnt lgkmcnt(0)
	v_mfma_f32_16x16x32_bf16 v[60:63], v[144:147], v[160:163], v[60:63]
	v_mfma_f32_16x16x32_bf16 v[56:59], v[152:155], v[160:163], v[56:59]
	v_mfma_f32_16x16x32_bf16 v[44:47], v[144:147], v[168:171], v[44:47]
	v_mfma_f32_16x16x32_bf16 v[40:43], v[152:155], v[168:171], v[40:43]
	v_mfma_f32_16x16x32_bf16 v[28:31], v[144:147], v[176:179], v[28:31]
	v_mfma_f32_16x16x32_bf16 v[24:27], v[152:155], v[176:179], v[24:27]
	v_mfma_f32_16x16x32_bf16 v[12:15], v[144:147], v[184:187], v[12:15]
	v_mfma_f32_16x16x32_bf16 v[8:11], v[152:155], v[184:187], v[8:11]
	v_mfma_f32_16x16x32_bf16 v[60:63], v[148:151], v[164:167], v[60:63]
	v_mfma_f32_16x16x32_bf16 v[56:59], v[156:159], v[164:167], v[56:59]
	v_mfma_f32_16x16x32_bf16 v[44:47], v[148:151], v[172:175], v[44:47]
	v_mfma_f32_16x16x32_bf16 v[40:43], v[156:159], v[172:175], v[40:43]
	v_mfma_f32_16x16x32_bf16 v[28:31], v[148:151], v[180:183], v[28:31]
	v_mfma_f32_16x16x32_bf16 v[24:27], v[156:159], v[180:183], v[24:27]
	v_mfma_f32_16x16x32_bf16 v[12:15], v[148:151], v[188:191], v[12:15]
	v_mfma_f32_16x16x32_bf16 v[8:11], v[156:159], v[188:191], v[8:11]
	s_setprio 0
	s_barrier
; #define PG8_STAGE(bufoff, gbase, voff) do { _Pragma("unroll") for (int _i = 0; _i < 2; ++_i) \
;         __builtin_amdgcn_global_load_lds((const unsigned*)((const char*)(gbase) + (voff)[_i]), (LAS unsigned*)(lds + (bufoff) + ldsw + _i * 8192), 16, 0, 0); } while (0)
; #define PG8_LDA(dst, b, h) do { _Pragma("unroll") for (int m = 0; m < 4; ++m) _Pragma("unroll") for (int k = 0; k < 2; ++k) dst[m][k] = *(const LAS bf16x8*)(lds + PG8_SA(b, h) + aoff + m * 2048 + k * 1024); } while (0)
; #define PG8_LDB(dst, b, h) do { _Pragma("unroll") for (int n = 0; n < 2; ++n) _Pragma("unroll") for (int k = 0; k < 2; ++k) dst[n][k] = *(const LAS bf16x8*)(lds + PG8_SB(b, h) + boff + n * 2048 + k * 1024); } while (0)
; #define PG8_WAIT_V(n) asm volatile("s_waitcnt vmcnt(" #n ")" ::: "memory")
; #define PG8_WAIT_L(n) asm volatile("s_waitcnt lgkmcnt(" #n ")" ::: "memory")
; #define PG8_BAR __builtin_amdgcn_s_barrier()
; #define PG8_SCHED __builtin_amdgcn_sched_barrier(0)
; template <class Epi>
; __device__ __forceinline__ void gemm_phase(LAS unsigned char* lds, const bf16_t* A, int lda, const bf16_t* Bt, int ldb, int M, int N, int K, int asel, const Epi& E, const int fixed_round = -1) {
;     ...
;             PG8_STAGE(PG8_SB(0, 1), b2 + hstepB, voffB);
;             PG8_WAIT_V(6); PG8_BAR; PG8_MMA(1, 1, At, B1); PG8_BAR;
;             PG8_LDB(B0, 1, 0); PG8_SCHED; PG8_LDA(At, 1, 0); PG8_STAGE(PG8_SA(0, 1), a2 + hstepA, voffA);
;             PG8_WAIT_L(8); PG8_BAR; PG8_WAIT_L(0); PG8_MMA(0, 0, At, B0); PG8_BAR; PG8_SCHED;
;             PG8_LDB(B1, 1, 1); PG8_STAGE(PG8_SB(1, 0), b3, voffB);
	s_add_u32 s50, s8, 0x200000
	s_addc_u32 s51, s9, 0
	s_mov_b32 m0, s43
	s_nop 0
	global_load_lds_dwordx4 v202, s[50:51]
	s_mov_b32 m0, s44
	s_nop 0
	global_load_lds_dwordx4 v116, s[50:51]
	s_waitcnt vmcnt(6)
	s_barrier
	s_setprio 1
	v_mfma_f32_16x16x32_bf16 v[52:55], v[192:195], v[160:163], v[52:55]
	v_mfma_f32_16x16x32_bf16 v[48:51], v[204:207], v[160:163], v[48:51]
	v_mfma_f32_16x16x32_bf16 v[36:39], v[192:195], v[168:171], v[36:39]
	v_mfma_f32_16x16x32_bf16 v[32:35], v[204:207], v[168:171], v[32:35]
	v_mfma_f32_16x16x32_bf16 v[20:23], v[192:195], v[176:179], v[20:23]
	v_mfma_f32_16x16x32_bf16 v[16:19], v[204:207], v[176:179], v[16:19]
	v_mfma_f32_16x16x32_bf16 v[4:7], v[192:195], v[184:187], v[4:7]
	v_mfma_f32_16x16x32_bf16 v[0:3], v[204:207], v[184:187], v[0:3]
	v_mfma_f32_16x16x32_bf16 v[52:55], v[196:199], v[164:167], v[52:55]
	v_mfma_f32_16x16x32_bf16 v[48:51], v[208:211], v[164:167], v[48:51]
	v_mfma_f32_16x16x32_bf16 v[36:39], v[196:199], v[172:175], v[36:39]
	v_mfma_f32_16x16x32_bf16 v[32:35], v[208:211], v[172:175], v[32:35]
	v_mfma_f32_16x16x32_bf16 v[20:23], v[196:199], v[180:183], v[20:23]
	v_mfma_f32_16x16x32_bf16 v[16:19], v[208:211], v[180:183], v[16:19]
	v_mfma_f32_16x16x32_bf16 v[4:7], v[196:199], v[188:191], v[4:7]
	v_mfma_f32_16x16x32_bf16 v[0:3], v[208:211], v[188:191], v[0:3]
	s_setprio 0
	s_barrier
	ds_read_b128 v[144:147], v125
	ds_read_b128 v[148:151], v125 offset:1024
	ds_read_b128 v[152:155], v125 offset:2048
	ds_read_b128 v[156:159], v125 offset:3072
	s_add_u32 s12, s12, 0x200000
	s_addc_u32 s13, s13, 0
	s_mov_b32 m0, s31
	ds_read_b128 v[160:163], v123 offset:32768
	ds_read_b128 v[164:167], v123 offset:33792
	ds_read_b128 v[168:171], v123 offset:34816
	ds_read_b128 v[172:175], v123 offset:35840
	ds_read_b128 v[176:179], v123 offset:36864
	ds_read_b128 v[180:183], v123 offset:37888
	ds_read_b128 v[184:187], v123 offset:38912
	ds_read_b128 v[188:191], v123 offset:39936
	global_load_lds_dwordx4 v112, s[12:13]
	s_mov_b32 m0, s33
	s_nop 0
	global_load_lds_dwordx4 v114, s[12:13]
	s_waitcnt lgkmcnt(8)
	s_barrier
	s_waitcnt lgkmcnt(0)
	s_setprio 1
	s_waitcnt lgkmcnt(0)
	v_mfma_f32_16x16x32_bf16 v[140:143], v[144:147], v[160:163], v[140:143]
	v_mfma_f32_16x16x32_bf16 v[136:139], v[152:155], v[160:163], v[136:139]
	v_mfma_f32_16x16x32_bf16 v[108:111], v[144:147], v[168:171], v[108:111]
	v_mfma_f32_16x16x32_bf16 v[104:107], v[152:155], v[168:171], v[104:107]
	v_mfma_f32_16x16x32_bf16 v[92:95], v[144:147], v[176:179], v[92:95]
	v_mfma_f32_16x16x32_bf16 v[88:91], v[152:155], v[176:179], v[88:91]
	v_mfma_f32_16x16x32_bf16 v[76:79], v[144:147], v[184:187], v[76:79]
	v_mfma_f32_16x16x32_bf16 v[72:75], v[152:155], v[184:187], v[72:75]
	v_mfma_f32_16x16x32_bf16 v[140:143], v[148:151], v[164:167], v[140:143]
	v_mfma_f32_16x16x32_bf16 v[136:139], v[156:159], v[164:167], v[136:139]
	v_mfma_f32_16x16x32_bf16 v[108:111], v[148:151], v[172:175], v[108:111]
	v_mfma_f32_16x16x32_bf16 v[104:107], v[156:159], v[172:175], v[104:107]
	v_mfma_f32_16x16x32_bf16 v[92:95], v[148:151], v[180:183], v[92:95]
	v_mfma_f32_16x16x32_bf16 v[88:91], v[156:159], v[180:183], v[88:91]
	v_mfma_f32_16x16x32_bf16 v[76:79], v[148:151], v[188:191], v[76:79]
	v_mfma_f32_16x16x32_bf16 v[72:75], v[156:159], v[188:191], v[72:75]
	s_setprio 0
	s_barrier
	s_mov_b32 m0, s45
	ds_read_b128 v[192:195], v126
	ds_read_b128 v[196:199], v126 offset:1024
	ds_read_b128 v[204:207], v126 offset:2048
	ds_read_b128 v[208:211], v126 offset:3072
	global_load_lds_dwordx4 v202, s[98:99]
	s_mov_b32 m0, s46
	s_nop 0
	global_load_lds_dwordx4 v116, s[98:99]
	s_barrier
; #define PG8_STAGE(bufoff, gbase, voff) do { _Pragma("unroll") for (int _i = 0; _i < 2; ++_i) \
;         __builtin_amdgcn_global_load_lds((const unsigned*)((const char*)(gbase) + (voff)[_i]), (LAS unsigned*)(lds + (bufoff) + ldsw + _i * 8192), 16, 0, 0); } while (0)
; #define PG8_LDA(dst, b, h) do { _Pragma("unroll") for (int m = 0; m < 4; ++m) _Pragma("unroll") for (int k = 0; k < 2; ++k) dst[m][k] = *(const LAS bf16x8*)(lds + PG8_SA(b, h) + aoff + m * 2048 + k * 1024); } while (0)
; #define PG8_WAIT_V(n) asm volatile("s_waitcnt vmcnt(" #n ")" ::: "memory")
; #define PG8_WAIT_L(n) asm volatile("s_waitcnt lgkmcnt(" #n ")" ::: "memory")
; #define PG8_BAR __builtin_amdgcn_s_barrier()
; #define PG8_SCHED __builtin_amdgcn_sched_barrier(0)
; template <class Epi>
; __device__ __forceinline__ void gemm_phase(LAS unsigned char* lds, const bf16_t* A, int lda, const bf16_t* Bt, int ldb, int M, int N, int K, int asel, const Epi& E, const int fixed_round = -1) {
;     ...
;             PG8_BAR; PG8_WAIT_L(0); PG8_MMA(0, 1, At, B1); PG8_BAR;
;             PG8_LDA(At, 1, 1); PG8_STAGE(PG8_SA(1, 0), a3, voffA);
;             PG8_BAR; PG8_WAIT_L(0); PG8_MMA(1, 0, At, B0); PG8_BAR; PG8_SCHED;
;             PG8_STAGE(PG8_SB(1, 1), b3 + hstepB, voffB);
;             PG8_WAIT_V(6); PG8_BAR; PG8_MMA(1, 1, At, B1); PG8_BAR;
;     ...
;     PG8_WAIT_V(0);
;     if (wr == 0) PG8_BAR;
;     PG8_BAR;
	s_waitcnt lgkmcnt(0)
	s_setprio 1
	s_waitcnt lgkmcnt(0)
	v_mfma_f32_16x16x32_bf16 v[132:135], v[192:195], v[160:163], v[132:135]
	v_mfma_f32_16x16x32_bf16 v[128:131], v[204:207], v[160:163], v[128:131]
	v_mfma_f32_16x16x32_bf16 v[100:103], v[192:195], v[168:171], v[100:103]
	v_mfma_f32_16x16x32_bf16 v[96:99], v[204:207], v[168:171], v[96:99]
	v_mfma_f32_16x16x32_bf16 v[84:87], v[192:195], v[176:179], v[84:87]
	v_mfma_f32_16x16x32_bf16 v[80:83], v[204:207], v[176:179], v[80:83]
	v_mfma_f32_16x16x32_bf16 v[68:71], v[192:195], v[184:187], v[68:71]
	v_mfma_f32_16x16x32_bf16 v[64:67], v[204:207], v[184:187], v[64:67]
	v_mfma_f32_16x16x32_bf16 v[132:135], v[196:199], v[164:167], v[132:135]
	v_mfma_f32_16x16x32_bf16 v[128:131], v[208:211], v[164:167], v[128:131]
	v_mfma_f32_16x16x32_bf16 v[100:103], v[196:199], v[172:175], v[100:103]
	v_mfma_f32_16x16x32_bf16 v[96:99], v[208:211], v[172:175], v[96:99]
	v_mfma_f32_16x16x32_bf16 v[84:87], v[196:199], v[180:183], v[84:87]
	v_mfma_f32_16x16x32_bf16 v[80:83], v[208:211], v[180:183], v[80:83]
	v_mfma_f32_16x16x32_bf16 v[68:71], v[196:199], v[188:191], v[68:71]
	v_mfma_f32_16x16x32_bf16 v[64:67], v[208:211], v[188:191], v[64:67]
	s_setprio 0
	s_mov_b32 m0, s36
	s_barrier
	ds_read_b128 v[160:163], v123 offset:49152
	ds_read_b128 v[164:167], v123 offset:50176
	ds_read_b128 v[168:171], v123 offset:51200
	ds_read_b128 v[172:175], v123 offset:52224
	ds_read_b128 v[176:179], v123 offset:53248
	ds_read_b128 v[180:183], v123 offset:54272
	ds_read_b128 v[184:187], v123 offset:55296
	ds_read_b128 v[188:191], v123 offset:56320
	global_load_lds_dwordx4 v112, s[100:101]
	s_mov_b32 m0, s37
	s_nop 0
	global_load_lds_dwordx4 v114, s[100:101]
	s_barrier
	s_waitcnt lgkmcnt(0)
	s_setprio 1
	s_waitcnt lgkmcnt(0)
	v_mfma_f32_16x16x32_bf16 v[60:63], v[144:147], v[160:163], v[60:63]
	v_mfma_f32_16x16x32_bf16 v[56:59], v[152:155], v[160:163], v[56:59]
	v_mfma_f32_16x16x32_bf16 v[44:47], v[144:147], v[168:171], v[44:47]
	v_mfma_f32_16x16x32_bf16 v[40:43], v[152:155], v[168:171], v[40:43]
	v_mfma_f32_16x16x32_bf16 v[28:31], v[144:147], v[176:179], v[28:31]
	v_mfma_f32_16x16x32_bf16 v[24:27], v[152:155], v[176:179], v[24:27]
	v_mfma_f32_16x16x32_bf16 v[12:15], v[144:147], v[184:187], v[12:15]
	v_mfma_f32_16x16x32_bf16 v[8:11], v[152:155], v[184:187], v[8:11]
	v_mfma_f32_16x16x32_bf16 v[60:63], v[148:151], v[164:167], v[60:63]
	v_mfma_f32_16x16x32_bf16 v[56:59], v[156:159], v[164:167], v[56:59]
	v_mfma_f32_16x16x32_bf16 v[44:47], v[148:151], v[172:175], v[44:47]
	v_mfma_f32_16x16x32_bf16 v[40:43], v[156:159], v[172:175], v[40:43]
	v_mfma_f32_16x16x32_bf16 v[28:31], v[148:151], v[180:183], v[28:31]
	v_mfma_f32_16x16x32_bf16 v[24:27], v[156:159], v[180:183], v[24:27]
	v_mfma_f32_16x16x32_bf16 v[12:15], v[148:151], v[188:191], v[12:15]
	v_mfma_f32_16x16x32_bf16 v[8:11], v[156:159], v[188:191], v[8:11]
	s_setprio 0
	s_barrier
	s_add_u32 s8, s8, 0x200080
	s_addc_u32 s9, s9, 0
	s_mov_b32 m0, s47
	s_nop 0
	global_load_lds_dwordx4 v202, s[8:9]
	s_mov_b32 m0, s48
	s_nop 0
	global_load_lds_dwordx4 v116, s[8:9]
	s_waitcnt vmcnt(6)
	s_barrier
	s_setprio 1
	v_mfma_f32_16x16x32_bf16 v[52:55], v[192:195], v[160:163], v[52:55]
	v_mfma_f32_16x16x32_bf16 v[48:51], v[204:207], v[160:163], v[48:51]
	v_mfma_f32_16x16x32_bf16 v[36:39], v[192:195], v[168:171], v[36:39]
	v_mfma_f32_16x16x32_bf16 v[32:35], v[204:207], v[168:171], v[32:35]
	v_mfma_f32_16x16x32_bf16 v[20:23], v[192:195], v[176:179], v[20:23]
	v_mfma_f32_16x16x32_bf16 v[16:19], v[204:207], v[176:179], v[16:19]
	v_mfma_f32_16x16x32_bf16 v[4:7], v[192:195], v[184:187], v[4:7]
	v_mfma_f32_16x16x32_bf16 v[0:3], v[204:207], v[184:187], v[0:3]
	v_mfma_f32_16x16x32_bf16 v[52:55], v[196:199], v[164:167], v[52:55]
	v_mfma_f32_16x16x32_bf16 v[48:51], v[208:211], v[164:167], v[48:51]
	v_mfma_f32_16x16x32_bf16 v[36:39], v[196:199], v[172:175], v[36:39]
	v_mfma_f32_16x16x32_bf16 v[32:35], v[208:211], v[172:175], v[32:35]
	v_mfma_f32_16x16x32_bf16 v[20:23], v[196:199], v[180:183], v[20:23]
	v_mfma_f32_16x16x32_bf16 v[16:19], v[208:211], v[180:183], v[16:19]
	v_mfma_f32_16x16x32_bf16 v[4:7], v[196:199], v[188:191], v[4:7]
	v_mfma_f32_16x16x32_bf16 v[0:3], v[208:211], v[188:191], v[0:3]
	s_setprio 0
	s_add_i32 s34, s34, 2
	s_add_u32 s6, s6, 0x100
	s_addc_u32 s7, s7, 0
	s_cmpk_lt_u32 s34, 0x7e
	s_cbranch_scc1 .Lrot_12
	s_barrier
	s_waitcnt vmcnt(0)
	s_cmpk_gt_u32 s18, 0xff
	s_cbranch_scc1 .LBB0_1325
	s_barrier
